# MFMA issue order inside each 16-MFMA block changed to snake order (consecutive MFMAs share one operand) to reduce operand toggling power
# speedup vs baseline: 1.0034x; 1.0034x over previous
; #define PG8_STAGE(bufoff, gbase, voff) do { _Pragma("unroll") for (int _i = 0; _i < 2; ++_i) \
;         __builtin_amdgcn_global_load_lds((const unsigned*)((const char*)(gbase) + (voff)[_i]), (PG8_LAS unsigned*)(lds + (bufoff) + ldsw + _i * 8192), 16, 0, 0); } while (0)
; #define PG8_LDA(dst, b, h) do { _Pragma("unroll") for (int m = 0; m < 4; ++m) _Pragma("unroll") for (int k = 0; k < 2; ++k) dst[m][k] = *(const PG8_LAS bf16x8*)(lds + PG8_SA(b, h) + aoff + m * 2048 + k * 1024); } while (0)
; #define PG8_LDB(dst, b, h) do { _Pragma("unroll") for (int n = 0; n < 2; ++n) _Pragma("unroll") for (int k = 0; k < 2; ++k) dst[n][k] = *(const PG8_LAS bf16x8*)(lds + PG8_SB(b, h) + boff + n * 2048 + k * 1024); } while (0)
; #define PG8_MMA(ai, bj, At, Bt) do { __builtin_amdgcn_s_setprio(1); _Pragma("unroll") for (int m = 0; m < 4; ++m) _Pragma("unroll") for (int n = 0; n < 2; ++n) _Pragma("unroll") for (int k = 0; k < 2; ++k) \
;         acc[ai][bj][m][n] = __builtin_amdgcn_mfma_f32_16x16x32_bf16(Bt[n][k], At[m][k], acc[ai][bj][m][n], 0, 0, 0); __builtin_amdgcn_s_setprio(0); } while (0)
; #define PG8_WAIT_V(n) asm volatile("s_waitcnt vmcnt(" #n ")" ::: "memory")
; #define PG8_WAIT_L(n) asm volatile("s_waitcnt lgkmcnt(" #n ")" ::: "memory")
; #define PG8_BAR __builtin_amdgcn_s_barrier()
; #define PG8_SCHED __builtin_amdgcn_sched_barrier(0)
; template <class Epi, class Sched, bool ALIGN_EPI = false, bool SP2 = false>
; __device__ __forceinline__ void gemm_phase(PG8_LAS unsigned char* lds, const Gemm g, const Sched& S, const Epi& E) {
;     ...
;             const bool last = (t == nt - 2);
;             const char* a1 = cA + (size_t)(t + 1) * kstep;
;             const char* a2 = last ? nA : cA + (size_t)(t + 2) * kstep; const char* b2 = last ? nB : cB + (size_t)(t + 2) * kstep;
;             const char* a3 = a2 + kstep; const char* b3 = b2 + kstep;
;             if (last && has_next) S.a_ready(nxt);
;             if constexpr (SP2) {
;             PG8_LDB(B0, 0, 0); PG8_LDB(B1, 0, 1); PG8_SCHED; PG8_LDA(At, 0, 0); PG8_STAGE(PG8_SA(1, 1), a1 + hstep, voffA);
;             PG8_WAIT_V(8); PG8_WAIT_L(0); PG8_BAR; PG8_MMA(0, 0, At, B0); PG8_MMA(0, 1, At, B1); PG8_BAR; PG8_SCHED;
;             PG8_LDA(At, 0, 1); PG8_STAGE(PG8_SB(0, 0), b2, voffB); PG8_STAGE(PG8_SB(0, 1), b2 + hstep, voffB); PG8_STAGE(PG8_SA(0, 0), a2, voffA);
.LBB0_68:
	ds_read_b128 v[128:131], v203
	ds_read_b128 v[132:135], v203 offset:1024
	ds_read_b128 v[136:139], v203 offset:2048
	ds_read_b128 v[140:143], v203 offset:3072
	ds_read_b128 v[144:147], v204
	ds_read_b128 v[148:151], v204 offset:1024
	ds_read_b128 v[180:183], v204 offset:2048
	ds_read_b128 v[184:187], v204 offset:3072
	s_add_u32 s30, s82, 0xfff80080
	s_addc_u32 s31, s83, -1
	s_cmp_eq_u32 s29, 28
	s_cselect_b32 s87, s1, s31
	s_cselect_b32 s86, s75, s30
	s_cselect_b32 s85, s73, vcc_hi
	s_cselect_b32 s84, s81, vcc_lo
	v_lshl_add_u64 v[152:153], s[82:83], 0, v[170:171]
	s_add_i32 m0, s94, 0xc000
	ds_read_b128 v[206:209], v205
	ds_read_b128 v[210:213], v205 offset:1024
	ds_read_b128 v[214:217], v205 offset:2048
	ds_read_b128 v[218:221], v205 offset:3072
	ds_read_b128 v[222:225], v205 offset:4096
	ds_read_b128 v[226:229], v205 offset:5120
	ds_read_b128 v[230:233], v205 offset:6144
	ds_read_b128 v[234:237], v205 offset:7168
	global_load_lds_dwordx4 v[152:153], off
	v_lshl_add_u64 v[152:153], s[82:83], 0, v[172:173]
	s_add_i32 m0, s94, 0xe000
	s_nop 0
	global_load_lds_dwordx4 v[152:153], off
	s_waitcnt vmcnt(8)
	s_waitcnt lgkmcnt(0)
	s_barrier
	s_setprio 1
	s_waitcnt lgkmcnt(0)
	v_mfma_f32_16x16x32_bf16 v[124:127], v[128:131], v[206:209], v[124:127]
	v_mfma_f32_16x16x32_bf16 v[120:123], v[136:139], v[206:209], v[120:123]
	v_mfma_f32_16x16x32_bf16 v[112:115], v[136:139], v[214:217], v[112:115]
	v_mfma_f32_16x16x32_bf16 v[116:119], v[128:131], v[214:217], v[116:119]
	v_mfma_f32_16x16x32_bf16 v[108:111], v[128:131], v[222:225], v[108:111]
	v_mfma_f32_16x16x32_bf16 v[104:107], v[136:139], v[222:225], v[104:107]
	v_mfma_f32_16x16x32_bf16 v[96:99], v[136:139], v[230:233], v[96:99]
	v_mfma_f32_16x16x32_bf16 v[100:103], v[128:131], v[230:233], v[100:103]
	v_mfma_f32_16x16x32_bf16 v[100:103], v[132:135], v[234:237], v[100:103]
	v_mfma_f32_16x16x32_bf16 v[96:99], v[140:143], v[234:237], v[96:99]
	v_mfma_f32_16x16x32_bf16 v[104:107], v[140:143], v[226:229], v[104:107]
	v_mfma_f32_16x16x32_bf16 v[108:111], v[132:135], v[226:229], v[108:111]
	v_mfma_f32_16x16x32_bf16 v[116:119], v[132:135], v[218:221], v[116:119]
	v_mfma_f32_16x16x32_bf16 v[112:115], v[140:143], v[218:221], v[112:115]
	v_mfma_f32_16x16x32_bf16 v[120:123], v[140:143], v[210:213], v[120:123]
	v_mfma_f32_16x16x32_bf16 v[124:127], v[132:135], v[210:213], v[124:127]
	s_setprio 0
	s_setprio 1
	v_mfma_f32_16x16x32_bf16 v[68:71], v[144:147], v[206:209], v[68:71]
	v_mfma_f32_16x16x32_bf16 v[64:67], v[180:183], v[206:209], v[64:67]
	v_mfma_f32_16x16x32_bf16 v[48:51], v[180:183], v[214:217], v[48:51]
	v_mfma_f32_16x16x32_bf16 v[52:55], v[144:147], v[214:217], v[52:55]
	v_mfma_f32_16x16x32_bf16 v[44:47], v[144:147], v[222:225], v[44:47]
	v_mfma_f32_16x16x32_bf16 v[40:43], v[180:183], v[222:225], v[40:43]
	v_mfma_f32_16x16x32_bf16 v[32:35], v[180:183], v[230:233], v[32:35]
	v_mfma_f32_16x16x32_bf16 v[36:39], v[144:147], v[230:233], v[36:39]
	v_mfma_f32_16x16x32_bf16 v[36:39], v[148:151], v[234:237], v[36:39]
	v_mfma_f32_16x16x32_bf16 v[32:35], v[184:187], v[234:237], v[32:35]
	v_mfma_f32_16x16x32_bf16 v[40:43], v[184:187], v[226:229], v[40:43]
	v_mfma_f32_16x16x32_bf16 v[44:47], v[148:151], v[226:229], v[44:47]
	v_mfma_f32_16x16x32_bf16 v[52:55], v[148:151], v[218:221], v[52:55]
	v_mfma_f32_16x16x32_bf16 v[48:51], v[184:187], v[218:221], v[48:51]
	v_mfma_f32_16x16x32_bf16 v[64:67], v[184:187], v[210:213], v[64:67]
	v_mfma_f32_16x16x32_bf16 v[68:71], v[148:151], v[210:213], v[68:71]
	s_setprio 0
	s_barrier
	s_add_i32 s30, s47, s92
	v_lshl_add_u64 v[152:153], s[84:85], 0, v[158:159]
	s_mov_b32 m0, s30
	ds_read_b128 v[206:209], v205 offset:16384
	ds_read_b128 v[210:213], v205 offset:17408
	ds_read_b128 v[214:217], v205 offset:18432
	ds_read_b128 v[218:221], v205 offset:19456
	ds_read_b128 v[222:225], v205 offset:20480
	ds_read_b128 v[226:229], v205 offset:21504
	ds_read_b128 v[230:233], v205 offset:22528
	ds_read_b128 v[234:237], v205 offset:23552
	global_load_lds_dwordx4 v[152:153], off
	s_add_i32 m0, s30, 0x2000
	s_add_u32 s30, s84, 0x80000
	v_lshl_add_u64 v[188:189], s[84:85], 0, v[154:155]
	s_addc_u32 s31, s85, 0
	s_add_i32 s89, s33, s92
	global_load_lds_dwordx4 v[188:189], off
	v_lshl_add_u64 v[238:239], s[30:31], 0, v[158:159]
	s_mov_b32 m0, s89
	v_lshl_add_u64 v[240:241], s[86:87], 0, v[156:157]
	global_load_lds_dwordx4 v[238:239], off
	v_lshl_add_u64 v[238:239], s[30:31], 0, v[154:155]
	s_add_i32 m0, s89, 0x2000
	s_nop 0
	global_load_lds_dwordx4 v[238:239], off
	v_lshl_add_u64 v[238:239], s[86:87], 0, v[160:161]
	s_mov_b32 m0, s94
	s_nop 0
	global_load_lds_dwordx4 v[238:239], off
	s_mov_b32 m0, s95
	s_nop 0
	global_load_lds_dwordx4 v[240:241], off
	s_waitcnt vmcnt(8)
	s_waitcnt lgkmcnt(0)
	s_barrier
; #define PG8_STAGE(bufoff, gbase, voff) do { _Pragma("unroll") for (int _i = 0; _i < 2; ++_i) \
;         __builtin_amdgcn_global_load_lds((const unsigned*)((const char*)(gbase) + (voff)[_i]), (PG8_LAS unsigned*)(lds + (bufoff) + ldsw + _i * 8192), 16, 0, 0); } while (0)
; #define PG8_LDA(dst, b, h) do { _Pragma("unroll") for (int m = 0; m < 4; ++m) _Pragma("unroll") for (int k = 0; k < 2; ++k) dst[m][k] = *(const PG8_LAS bf16x8*)(lds + PG8_SA(b, h) + aoff + m * 2048 + k * 1024); } while (0)
; #define PG8_LDB(dst, b, h) do { _Pragma("unroll") for (int n = 0; n < 2; ++n) _Pragma("unroll") for (int k = 0; k < 2; ++k) dst[n][k] = *(const PG8_LAS bf16x8*)(lds + PG8_SB(b, h) + boff + n * 2048 + k * 1024); } while (0)
; #define PG8_MMA(ai, bj, At, Bt) do { __builtin_amdgcn_s_setprio(1); _Pragma("unroll") for (int m = 0; m < 4; ++m) _Pragma("unroll") for (int n = 0; n < 2; ++n) _Pragma("unroll") for (int k = 0; k < 2; ++k) \
;         acc[ai][bj][m][n] = __builtin_amdgcn_mfma_f32_16x16x32_bf16(Bt[n][k], At[m][k], acc[ai][bj][m][n], 0, 0, 0); __builtin_amdgcn_s_setprio(0); } while (0)
; #define PG8_WAIT_V(n) asm volatile("s_waitcnt vmcnt(" #n ")" ::: "memory")
; #define PG8_WAIT_L(n) asm volatile("s_waitcnt lgkmcnt(" #n ")" ::: "memory")
; #define PG8_BAR __builtin_amdgcn_s_barrier()
; #define PG8_SCHED __builtin_amdgcn_sched_barrier(0)
; template <class Epi, class Sched, bool ALIGN_EPI = false, bool SP2 = false>
; __device__ __forceinline__ void gemm_phase(PG8_LAS unsigned char* lds, const Gemm g, const Sched& S, const Epi& E) {
;     ...
;             PG8_WAIT_V(8); PG8_WAIT_L(0); PG8_BAR; PG8_MMA(1, 0, At, B0); PG8_MMA(1, 1, At, B1); PG8_BAR; PG8_SCHED;
;             PG8_LDB(B0, 1, 0); PG8_LDB(B1, 1, 1); PG8_SCHED; PG8_LDA(At, 1, 0); PG8_STAGE(PG8_SA(0, 1), a2 + hstep, voffA);
;             PG8_WAIT_V(8); PG8_WAIT_L(0); PG8_BAR; PG8_MMA(0, 0, At, B0); PG8_MMA(0, 1, At, B1); PG8_BAR; PG8_SCHED;
	s_setprio 1
	s_waitcnt lgkmcnt(0)
	v_mfma_f32_16x16x32_bf16 v[92:95], v[128:131], v[206:209], v[92:95]
	v_mfma_f32_16x16x32_bf16 v[88:91], v[136:139], v[206:209], v[88:91]
	v_mfma_f32_16x16x32_bf16 v[80:83], v[136:139], v[214:217], v[80:83]
	v_mfma_f32_16x16x32_bf16 v[84:87], v[128:131], v[214:217], v[84:87]
	v_mfma_f32_16x16x32_bf16 v[76:79], v[128:131], v[222:225], v[76:79]
	v_mfma_f32_16x16x32_bf16 v[72:75], v[136:139], v[222:225], v[72:75]
	v_mfma_f32_16x16x32_bf16 v[56:59], v[136:139], v[230:233], v[56:59]
	v_mfma_f32_16x16x32_bf16 v[60:63], v[128:131], v[230:233], v[60:63]
	v_mfma_f32_16x16x32_bf16 v[60:63], v[132:135], v[234:237], v[60:63]
	v_mfma_f32_16x16x32_bf16 v[56:59], v[140:143], v[234:237], v[56:59]
	v_mfma_f32_16x16x32_bf16 v[72:75], v[140:143], v[226:229], v[72:75]
	v_mfma_f32_16x16x32_bf16 v[76:79], v[132:135], v[226:229], v[76:79]
	v_mfma_f32_16x16x32_bf16 v[84:87], v[132:135], v[218:221], v[84:87]
	v_mfma_f32_16x16x32_bf16 v[80:83], v[140:143], v[218:221], v[80:83]
	v_mfma_f32_16x16x32_bf16 v[88:91], v[140:143], v[210:213], v[88:91]
	v_mfma_f32_16x16x32_bf16 v[92:95], v[132:135], v[210:213], v[92:95]
	s_setprio 0
	s_setprio 1
	v_mfma_f32_16x16x32_bf16 v[28:31], v[144:147], v[206:209], v[28:31]
	v_mfma_f32_16x16x32_bf16 v[24:27], v[180:183], v[206:209], v[24:27]
	v_mfma_f32_16x16x32_bf16 v[16:19], v[180:183], v[214:217], v[16:19]
	v_mfma_f32_16x16x32_bf16 v[20:23], v[144:147], v[214:217], v[20:23]
	v_mfma_f32_16x16x32_bf16 v[12:15], v[144:147], v[222:225], v[12:15]
	v_mfma_f32_16x16x32_bf16 v[8:11], v[180:183], v[222:225], v[8:11]
	v_mfma_f32_16x16x32_bf16 v[0:3], v[180:183], v[230:233], v[0:3]
	v_mfma_f32_16x16x32_bf16 v[4:7], v[144:147], v[230:233], v[4:7]
	v_mfma_f32_16x16x32_bf16 v[4:7], v[148:151], v[234:237], v[4:7]
	v_mfma_f32_16x16x32_bf16 v[0:3], v[184:187], v[234:237], v[0:3]
	v_mfma_f32_16x16x32_bf16 v[8:11], v[184:187], v[226:229], v[8:11]
	v_mfma_f32_16x16x32_bf16 v[12:15], v[148:151], v[226:229], v[12:15]
	v_mfma_f32_16x16x32_bf16 v[20:23], v[148:151], v[218:221], v[20:23]
	v_mfma_f32_16x16x32_bf16 v[16:19], v[184:187], v[218:221], v[16:19]
	v_mfma_f32_16x16x32_bf16 v[24:27], v[184:187], v[210:213], v[24:27]
	v_mfma_f32_16x16x32_bf16 v[28:31], v[148:151], v[210:213], v[28:31]
	s_setprio 0
	s_barrier
	s_add_i32 s89, 0, 0x18000
	s_add_i32 s54, 0, 0x1c000
	v_add_u32_e32 v140, s89, v190
	v_add_u32_e32 v162, s54, v190
	ds_read_b128 v[128:131], v140
	ds_read_b128 v[132:135], v140 offset:1024
	ds_read_b128 v[136:139], v140 offset:2048
	ds_read_b128 v[140:143], v140 offset:3072
	ds_read_b128 v[144:147], v162
	ds_read_b128 v[148:151], v162 offset:1024
	ds_read_b128 v[180:183], v162 offset:2048
	ds_read_b128 v[184:187], v162 offset:3072
	s_add_u32 s30, s86, 0x80000
	s_addc_u32 s31, s87, 0
	s_mov_b32 m0, s96
	v_lshl_add_u64 v[242:243], s[30:31], 0, v[160:161]
	ds_read_b128 v[206:209], v205 offset:32768
	ds_read_b128 v[210:213], v205 offset:33792
	ds_read_b128 v[214:217], v205 offset:34816
	ds_read_b128 v[218:221], v205 offset:35840
	ds_read_b128 v[222:225], v205 offset:36864
	ds_read_b128 v[226:229], v205 offset:37888
	ds_read_b128 v[230:233], v205 offset:38912
	ds_read_b128 v[234:237], v205 offset:39936
	global_load_lds_dwordx4 v[242:243], off
	v_lshl_add_u64 v[242:243], s[30:31], 0, v[156:157]
	s_mov_b32 m0, s97
	s_nop 0
	global_load_lds_dwordx4 v[242:243], off
	s_waitcnt vmcnt(8)
	s_waitcnt lgkmcnt(0)
	s_barrier
	s_setprio 1
	s_waitcnt lgkmcnt(0)
	v_mfma_f32_16x16x32_bf16 v[124:127], v[128:131], v[206:209], v[124:127]
	v_mfma_f32_16x16x32_bf16 v[120:123], v[136:139], v[206:209], v[120:123]
	v_mfma_f32_16x16x32_bf16 v[112:115], v[136:139], v[214:217], v[112:115]
	v_mfma_f32_16x16x32_bf16 v[116:119], v[128:131], v[214:217], v[116:119]
	v_mfma_f32_16x16x32_bf16 v[108:111], v[128:131], v[222:225], v[108:111]
	v_mfma_f32_16x16x32_bf16 v[104:107], v[136:139], v[222:225], v[104:107]
	v_mfma_f32_16x16x32_bf16 v[96:99], v[136:139], v[230:233], v[96:99]
	v_mfma_f32_16x16x32_bf16 v[100:103], v[128:131], v[230:233], v[100:103]
	v_mfma_f32_16x16x32_bf16 v[100:103], v[132:135], v[234:237], v[100:103]
	v_mfma_f32_16x16x32_bf16 v[96:99], v[140:143], v[234:237], v[96:99]
	v_mfma_f32_16x16x32_bf16 v[104:107], v[140:143], v[226:229], v[104:107]
	v_mfma_f32_16x16x32_bf16 v[108:111], v[132:135], v[226:229], v[108:111]
	v_mfma_f32_16x16x32_bf16 v[116:119], v[132:135], v[218:221], v[116:119]
	v_mfma_f32_16x16x32_bf16 v[112:115], v[140:143], v[218:221], v[112:115]
	v_mfma_f32_16x16x32_bf16 v[120:123], v[140:143], v[210:213], v[120:123]
	v_mfma_f32_16x16x32_bf16 v[124:127], v[132:135], v[210:213], v[124:127]
	s_setprio 0
	s_setprio 1
	v_mfma_f32_16x16x32_bf16 v[68:71], v[144:147], v[206:209], v[68:71]
	v_mfma_f32_16x16x32_bf16 v[64:67], v[180:183], v[206:209], v[64:67]
	v_mfma_f32_16x16x32_bf16 v[48:51], v[180:183], v[214:217], v[48:51]
	v_mfma_f32_16x16x32_bf16 v[52:55], v[144:147], v[214:217], v[52:55]
	v_mfma_f32_16x16x32_bf16 v[44:47], v[144:147], v[222:225], v[44:47]
	v_mfma_f32_16x16x32_bf16 v[40:43], v[180:183], v[222:225], v[40:43]
	v_mfma_f32_16x16x32_bf16 v[32:35], v[180:183], v[230:233], v[32:35]
	v_mfma_f32_16x16x32_bf16 v[36:39], v[144:147], v[230:233], v[36:39]
	v_mfma_f32_16x16x32_bf16 v[36:39], v[148:151], v[234:237], v[36:39]
	v_mfma_f32_16x16x32_bf16 v[32:35], v[184:187], v[234:237], v[32:35]
	v_mfma_f32_16x16x32_bf16 v[40:43], v[184:187], v[226:229], v[40:43]
	v_mfma_f32_16x16x32_bf16 v[44:47], v[148:151], v[226:229], v[44:47]
	v_mfma_f32_16x16x32_bf16 v[52:55], v[148:151], v[218:221], v[52:55]
	v_mfma_f32_16x16x32_bf16 v[48:51], v[184:187], v[218:221], v[48:51]
	v_mfma_f32_16x16x32_bf16 v[64:67], v[184:187], v[210:213], v[64:67]
	v_mfma_f32_16x16x32_bf16 v[68:71], v[148:151], v[210:213], v[68:71]
	s_setprio 0
	s_barrier
; #define PG8_STAGE(bufoff, gbase, voff) do { _Pragma("unroll") for (int _i = 0; _i < 2; ++_i) \
;         __builtin_amdgcn_global_load_lds((const unsigned*)((const char*)(gbase) + (voff)[_i]), (PG8_LAS unsigned*)(lds + (bufoff) + ldsw + _i * 8192), 16, 0, 0); } while (0)
; #define PG8_LDA(dst, b, h) do { _Pragma("unroll") for (int m = 0; m < 4; ++m) _Pragma("unroll") for (int k = 0; k < 2; ++k) dst[m][k] = *(const PG8_LAS bf16x8*)(lds + PG8_SA(b, h) + aoff + m * 2048 + k * 1024); } while (0)
; #define PG8_MMA(ai, bj, At, Bt) do { __builtin_amdgcn_s_setprio(1); _Pragma("unroll") for (int m = 0; m < 4; ++m) _Pragma("unroll") for (int n = 0; n < 2; ++n) _Pragma("unroll") for (int k = 0; k < 2; ++k) \
;         acc[ai][bj][m][n] = __builtin_amdgcn_mfma_f32_16x16x32_bf16(Bt[n][k], At[m][k], acc[ai][bj][m][n], 0, 0, 0); __builtin_amdgcn_s_setprio(0); } while (0)
; #define PG8_WAIT_V(n) asm volatile("s_waitcnt vmcnt(" #n ")" ::: "memory")
; #define PG8_WAIT_L(n) asm volatile("s_waitcnt lgkmcnt(" #n ")" ::: "memory")
; #define PG8_BAR __builtin_amdgcn_s_barrier()
; #define PG8_SCHED __builtin_amdgcn_sched_barrier(0)
; template <class Epi, class Sched, bool ALIGN_EPI = false, bool SP2 = false>
; __device__ __forceinline__ void gemm_phase(PG8_LAS unsigned char* lds, const Gemm g, const Sched& S, const Epi& E) {
;     ...
;         for (int t = 0; t < nt; t += 2) {
;             const bool last = (t == nt - 2);
;             const char* a1 = cA + (size_t)(t + 1) * kstep;
;             const char* a2 = last ? nA : cA + (size_t)(t + 2) * kstep; const char* b2 = last ? nB : cB + (size_t)(t + 2) * kstep;
;     ...
;             PG8_LDA(At, 1, 1); PG8_STAGE(PG8_SB(1, 0), b3, voffB); PG8_STAGE(PG8_SB(1, 1), b3 + hstep, voffB); PG8_STAGE(PG8_SA(1, 0), a3, voffA);
;             PG8_WAIT_V(8); PG8_WAIT_L(0); PG8_BAR; PG8_MMA(1, 0, At, B0); PG8_MMA(1, 1, At, B1); PG8_BAR; PG8_SCHED;
	s_add_i32 s30, s89, s92
	v_lshl_add_u64 v[152:153], v[152:153], 0, s[62:63]
	s_mov_b32 m0, s30
	ds_read_b128 v[206:209], v205 offset:49152
	ds_read_b128 v[210:213], v205 offset:50176
	ds_read_b128 v[214:217], v205 offset:51200
	ds_read_b128 v[218:221], v205 offset:52224
	ds_read_b128 v[222:225], v205 offset:53248
	ds_read_b128 v[226:229], v205 offset:54272
	ds_read_b128 v[230:233], v205 offset:55296
	ds_read_b128 v[234:237], v205 offset:56320
	global_load_lds_dwordx4 v[152:153], off
	s_add_i32 m0, s30, 0x2000
	s_add_u32 s30, s84, 0x80080
	v_lshl_add_u64 v[152:153], v[188:189], 0, s[62:63]
	s_addc_u32 s31, s85, 0
	s_add_i32 s54, s54, s92
	global_load_lds_dwordx4 v[152:153], off
	v_lshl_add_u64 v[152:153], s[30:31], 0, v[158:159]
	s_mov_b32 m0, s54
	s_nop 0
	global_load_lds_dwordx4 v[152:153], off
	v_lshl_add_u64 v[152:153], s[30:31], 0, v[154:155]
	s_add_i32 m0, s54, 0x2000
	s_nop 0
	global_load_lds_dwordx4 v[152:153], off
	v_lshl_add_u64 v[152:153], v[238:239], 0, s[62:63]
	s_mov_b32 m0, s88
	s_nop 0
	global_load_lds_dwordx4 v[152:153], off
	v_lshl_add_u64 v[152:153], v[240:241], 0, s[62:63]
	s_mov_b32 m0, s46
	s_nop 0
	global_load_lds_dwordx4 v[152:153], off
	s_waitcnt vmcnt(8)
	s_waitcnt lgkmcnt(0)
	s_barrier
	s_setprio 1
	s_waitcnt lgkmcnt(0)
	v_mfma_f32_16x16x32_bf16 v[92:95], v[128:131], v[206:209], v[92:95]
	v_mfma_f32_16x16x32_bf16 v[88:91], v[136:139], v[206:209], v[88:91]
	v_mfma_f32_16x16x32_bf16 v[80:83], v[136:139], v[214:217], v[80:83]
	v_mfma_f32_16x16x32_bf16 v[84:87], v[128:131], v[214:217], v[84:87]
	v_mfma_f32_16x16x32_bf16 v[76:79], v[128:131], v[222:225], v[76:79]
	v_mfma_f32_16x16x32_bf16 v[72:75], v[136:139], v[222:225], v[72:75]
	v_mfma_f32_16x16x32_bf16 v[56:59], v[136:139], v[230:233], v[56:59]
	v_mfma_f32_16x16x32_bf16 v[60:63], v[128:131], v[230:233], v[60:63]
	v_mfma_f32_16x16x32_bf16 v[60:63], v[132:135], v[234:237], v[60:63]
	v_mfma_f32_16x16x32_bf16 v[56:59], v[140:143], v[234:237], v[56:59]
	v_mfma_f32_16x16x32_bf16 v[72:75], v[140:143], v[226:229], v[72:75]
	v_mfma_f32_16x16x32_bf16 v[76:79], v[132:135], v[226:229], v[76:79]
	v_mfma_f32_16x16x32_bf16 v[84:87], v[132:135], v[218:221], v[84:87]
	v_mfma_f32_16x16x32_bf16 v[80:83], v[140:143], v[218:221], v[80:83]
	v_mfma_f32_16x16x32_bf16 v[88:91], v[140:143], v[210:213], v[88:91]
	v_mfma_f32_16x16x32_bf16 v[92:95], v[132:135], v[210:213], v[92:95]
	s_setprio 0
	s_setprio 1
	v_mfma_f32_16x16x32_bf16 v[28:31], v[144:147], v[206:209], v[28:31]
	v_mfma_f32_16x16x32_bf16 v[24:27], v[180:183], v[206:209], v[24:27]
	v_mfma_f32_16x16x32_bf16 v[16:19], v[180:183], v[214:217], v[16:19]
	v_mfma_f32_16x16x32_bf16 v[20:23], v[144:147], v[214:217], v[20:23]
	v_mfma_f32_16x16x32_bf16 v[12:15], v[144:147], v[222:225], v[12:15]
	v_mfma_f32_16x16x32_bf16 v[8:11], v[180:183], v[222:225], v[8:11]
	v_mfma_f32_16x16x32_bf16 v[0:3], v[180:183], v[230:233], v[0:3]
	v_mfma_f32_16x16x32_bf16 v[4:7], v[144:147], v[230:233], v[4:7]
	v_mfma_f32_16x16x32_bf16 v[4:7], v[148:151], v[234:237], v[4:7]
	v_mfma_f32_16x16x32_bf16 v[0:3], v[184:187], v[234:237], v[0:3]
	v_mfma_f32_16x16x32_bf16 v[8:11], v[184:187], v[226:229], v[8:11]
	v_mfma_f32_16x16x32_bf16 v[12:15], v[148:151], v[226:229], v[12:15]
	v_mfma_f32_16x16x32_bf16 v[20:23], v[148:151], v[218:221], v[20:23]
	v_mfma_f32_16x16x32_bf16 v[16:19], v[184:187], v[218:221], v[16:19]
	v_mfma_f32_16x16x32_bf16 v[24:27], v[184:187], v[210:213], v[24:27]
	v_mfma_f32_16x16x32_bf16 v[28:31], v[148:151], v[210:213], v[28:31]
	s_setprio 0
	s_barrier
	s_add_i32 s29, s29, 2
	s_add_u32 s82, s82, 0x100
	s_addc_u32 s83, s83, 0
	s_add_u32 vcc_lo, vcc_lo, 0x100
	s_addc_u32 vcc_hi, vcc_hi, 0
	s_cmp_gt_u32 s29, 29
	s_cbranch_scc0 .LBB0_68
	s_and_b64 vcc, exec, s[64:65]
	s_cbranch_vccz .LBB0_71
	s_barrier

; #define PG8_STAGE(bufoff, gbase, voff) do { _Pragma("unroll") for (int _i = 0; _i < 2; ++_i) \
;         __builtin_amdgcn_global_load_lds((const unsigned*)((const char*)(gbase) + (voff)[_i]), (PG8_LAS unsigned*)(lds + (bufoff) + ldsw + _i * 8192), 16, 0, 0); } while (0)
; #define PG8_LDA(dst, b, h) do { _Pragma("unroll") for (int m = 0; m < 4; ++m) _Pragma("unroll") for (int k = 0; k < 2; ++k) dst[m][k] = *(const PG8_LAS bf16x8*)(lds + PG8_SA(b, h) + aoff + m * 2048 + k * 1024); } while (0)
; #define PG8_LDB(dst, b, h) do { _Pragma("unroll") for (int n = 0; n < 2; ++n) _Pragma("unroll") for (int k = 0; k < 2; ++k) dst[n][k] = *(const PG8_LAS bf16x8*)(lds + PG8_SB(b, h) + boff + n * 2048 + k * 1024); } while (0)
; #define PG8_MMA(ai, bj, At, Bt) do { __builtin_amdgcn_s_setprio(1); _Pragma("unroll") for (int m = 0; m < 4; ++m) _Pragma("unroll") for (int n = 0; n < 2; ++n) _Pragma("unroll") for (int k = 0; k < 2; ++k) \
;         acc[ai][bj][m][n] = __builtin_amdgcn_mfma_f32_16x16x32_bf16(Bt[n][k], At[m][k], acc[ai][bj][m][n], 0, 0, 0); __builtin_amdgcn_s_setprio(0); } while (0)
; #define PG8_WAIT_V(n) asm volatile("s_waitcnt vmcnt(" #n ")" ::: "memory")
; #define PG8_WAIT_L(n) asm volatile("s_waitcnt lgkmcnt(" #n ")" ::: "memory")
; #define PG8_BAR __builtin_amdgcn_s_barrier()
; #define PG8_SCHED __builtin_amdgcn_sched_barrier(0)
; template <class Epi, class Sched, bool ALIGN_EPI = false, bool SP2 = false>
; __device__ __forceinline__ void gemm_phase(PG8_LAS unsigned char* lds, const Gemm g, const Sched& S, const Epi& E) {
;     ...
;             const bool last = (t == nt - 2);
;             const char* a1 = cA + (size_t)(t + 1) * kstep;
;             const char* a2 = last ? nA : cA + (size_t)(t + 2) * kstep; const char* b2 = last ? nB : cB + (size_t)(t + 2) * kstep;
;             const char* a3 = a2 + kstep; const char* b3 = b2 + kstep;
;             if (last && has_next) S.a_ready(nxt);
;             if constexpr (SP2) {
;             PG8_LDB(B0, 0, 0); PG8_LDB(B1, 0, 1); PG8_SCHED; PG8_LDA(At, 0, 0); PG8_STAGE(PG8_SA(1, 1), a1 + hstep, voffA);
;             PG8_WAIT_V(8); PG8_WAIT_L(0); PG8_BAR; PG8_MMA(0, 0, At, B0); PG8_MMA(0, 1, At, B1); PG8_BAR; PG8_SCHED;
;             PG8_LDA(At, 0, 1); PG8_STAGE(PG8_SB(0, 0), b2, voffB); PG8_STAGE(PG8_SB(0, 1), b2 + hstep, voffB); PG8_STAGE(PG8_SA(0, 0), a2, voffA);
.LBB0_283:
	ds_read_b128 v[152:155], v149
	ds_read_b128 v[156:159], v149 offset:1024
	ds_read_b128 v[160:163], v149 offset:2048
	ds_read_b128 v[164:167], v149 offset:3072
	ds_read_b128 v[168:171], v150
	ds_read_b128 v[172:175], v150 offset:1024
	ds_read_b128 v[180:183], v150 offset:2048
	ds_read_b128 v[184:187], v150 offset:3072
	s_add_u32 s30, s66, 0xfff80080
	s_addc_u32 s31, s67, -1
	s_cmp_eq_u32 s85, 28
	s_cselect_b32 s71, s59, s31
	s_cselect_b32 s70, s81, s30
	s_cselect_b32 s69, s57, s84
	s_cselect_b32 s68, s82, s83
	v_lshl_add_u64 v[144:145], s[66:67], 0, v[136:137]
	s_add_i32 m0, s29, 0xc000
	ds_read_b128 v[188:191], v151
	ds_read_b128 v[192:195], v151 offset:1024
	ds_read_b128 v[196:199], v151 offset:2048
	ds_read_b128 v[200:203], v151 offset:3072
	ds_read_b128 v[204:207], v151 offset:4096
	ds_read_b128 v[208:211], v151 offset:5120
	ds_read_b128 v[212:215], v151 offset:6144
	ds_read_b128 v[216:219], v151 offset:7168
	global_load_lds_dwordx4 v[144:145], off
	v_lshl_add_u64 v[144:145], s[66:67], 0, v[138:139]
	s_add_i32 m0, s29, 0xe000
	s_nop 0
	global_load_lds_dwordx4 v[144:145], off
	s_waitcnt vmcnt(8)
	s_waitcnt lgkmcnt(0)
	s_barrier
	s_setprio 1
	s_waitcnt lgkmcnt(0)
	v_mfma_f32_16x16x32_bf16 v[124:127], v[152:155], v[188:191], v[124:127]
	v_mfma_f32_16x16x32_bf16 v[120:123], v[160:163], v[188:191], v[120:123]
	v_mfma_f32_16x16x32_bf16 v[108:111], v[160:163], v[196:199], v[108:111]
	v_mfma_f32_16x16x32_bf16 v[116:119], v[152:155], v[196:199], v[116:119]
	v_mfma_f32_16x16x32_bf16 v[100:103], v[152:155], v[204:207], v[100:103]
	v_mfma_f32_16x16x32_bf16 v[92:95], v[160:163], v[204:207], v[92:95]
	v_mfma_f32_16x16x32_bf16 v[76:79], v[160:163], v[212:215], v[76:79]
	v_mfma_f32_16x16x32_bf16 v[84:87], v[152:155], v[212:215], v[84:87]
	v_mfma_f32_16x16x32_bf16 v[84:87], v[156:159], v[216:219], v[84:87]
	v_mfma_f32_16x16x32_bf16 v[76:79], v[164:167], v[216:219], v[76:79]
	v_mfma_f32_16x16x32_bf16 v[92:95], v[164:167], v[208:211], v[92:95]
	v_mfma_f32_16x16x32_bf16 v[100:103], v[156:159], v[208:211], v[100:103]
	v_mfma_f32_16x16x32_bf16 v[116:119], v[156:159], v[200:203], v[116:119]
	v_mfma_f32_16x16x32_bf16 v[108:111], v[164:167], v[200:203], v[108:111]
	v_mfma_f32_16x16x32_bf16 v[120:123], v[164:167], v[192:195], v[120:123]
	v_mfma_f32_16x16x32_bf16 v[124:127], v[156:159], v[192:195], v[124:127]
	s_setprio 0
	s_setprio 1
	v_mfma_f32_16x16x32_bf16 v[112:115], v[168:171], v[188:191], v[112:115]
	v_mfma_f32_16x16x32_bf16 v[104:107], v[180:183], v[188:191], v[104:107]
	v_mfma_f32_16x16x32_bf16 v[88:91], v[180:183], v[196:199], v[88:91]
	v_mfma_f32_16x16x32_bf16 v[96:99], v[168:171], v[196:199], v[96:99]
	v_mfma_f32_16x16x32_bf16 v[80:83], v[168:171], v[204:207], v[80:83]
	v_mfma_f32_16x16x32_bf16 v[72:75], v[180:183], v[204:207], v[72:75]
	v_mfma_f32_16x16x32_bf16 v[64:67], v[180:183], v[212:215], v[64:67]
	v_mfma_f32_16x16x32_bf16 v[68:71], v[168:171], v[212:215], v[68:71]
	v_mfma_f32_16x16x32_bf16 v[68:71], v[172:175], v[216:219], v[68:71]
	v_mfma_f32_16x16x32_bf16 v[64:67], v[184:187], v[216:219], v[64:67]
	v_mfma_f32_16x16x32_bf16 v[72:75], v[184:187], v[208:211], v[72:75]
	v_mfma_f32_16x16x32_bf16 v[80:83], v[172:175], v[208:211], v[80:83]
	v_mfma_f32_16x16x32_bf16 v[96:99], v[172:175], v[200:203], v[96:99]
	v_mfma_f32_16x16x32_bf16 v[88:91], v[184:187], v[200:203], v[88:91]
	v_mfma_f32_16x16x32_bf16 v[104:107], v[184:187], v[192:195], v[104:107]
	v_mfma_f32_16x16x32_bf16 v[112:115], v[172:175], v[192:195], v[112:115]
	s_setprio 0
	s_barrier
	s_add_i32 s30, s74, s1
	v_lshl_add_u64 v[144:145], s[68:69], 0, v[130:131]
	s_mov_b32 m0, s30
	ds_read_b128 v[188:191], v151 offset:16384
	ds_read_b128 v[192:195], v151 offset:17408
	ds_read_b128 v[196:199], v151 offset:18432
	ds_read_b128 v[200:203], v151 offset:19456
	ds_read_b128 v[204:207], v151 offset:20480
	ds_read_b128 v[208:211], v151 offset:21504
	ds_read_b128 v[212:215], v151 offset:22528
	ds_read_b128 v[216:219], v151 offset:23552
	global_load_lds_dwordx4 v[144:145], off
	s_add_i32 m0, s30, 0x2000
	s_add_u32 s30, s68, 0x80000
	v_lshl_add_u64 v[176:177], s[68:69], 0, v[134:135]
	s_addc_u32 s31, s69, 0
	s_add_i32 s86, s75, s1
	global_load_lds_dwordx4 v[176:177], off
	v_lshl_add_u64 v[220:221], s[30:31], 0, v[130:131]
	s_mov_b32 m0, s86
	v_lshl_add_u64 v[222:223], s[70:71], 0, v[132:133]
	global_load_lds_dwordx4 v[220:221], off
	v_lshl_add_u64 v[220:221], s[30:31], 0, v[134:135]
	s_add_i32 m0, s86, 0x2000
	s_nop 0
	global_load_lds_dwordx4 v[220:221], off
	v_lshl_add_u64 v[220:221], s[70:71], 0, v[128:129]
	s_mov_b32 m0, s29
	s_nop 0
	global_load_lds_dwordx4 v[220:221], off
	s_mov_b32 m0, s33
	s_nop 0
	global_load_lds_dwordx4 v[222:223], off
	s_waitcnt vmcnt(8)
	s_waitcnt lgkmcnt(0)
	s_barrier
; #define PG8_STAGE(bufoff, gbase, voff) do { _Pragma("unroll") for (int _i = 0; _i < 2; ++_i) \
;         __builtin_amdgcn_global_load_lds((const unsigned*)((const char*)(gbase) + (voff)[_i]), (PG8_LAS unsigned*)(lds + (bufoff) + ldsw + _i * 8192), 16, 0, 0); } while (0)
; #define PG8_LDA(dst, b, h) do { _Pragma("unroll") for (int m = 0; m < 4; ++m) _Pragma("unroll") for (int k = 0; k < 2; ++k) dst[m][k] = *(const PG8_LAS bf16x8*)(lds + PG8_SA(b, h) + aoff + m * 2048 + k * 1024); } while (0)
; #define PG8_LDB(dst, b, h) do { _Pragma("unroll") for (int n = 0; n < 2; ++n) _Pragma("unroll") for (int k = 0; k < 2; ++k) dst[n][k] = *(const PG8_LAS bf16x8*)(lds + PG8_SB(b, h) + boff + n * 2048 + k * 1024); } while (0)
; #define PG8_MMA(ai, bj, At, Bt) do { __builtin_amdgcn_s_setprio(1); _Pragma("unroll") for (int m = 0; m < 4; ++m) _Pragma("unroll") for (int n = 0; n < 2; ++n) _Pragma("unroll") for (int k = 0; k < 2; ++k) \
;         acc[ai][bj][m][n] = __builtin_amdgcn_mfma_f32_16x16x32_bf16(Bt[n][k], At[m][k], acc[ai][bj][m][n], 0, 0, 0); __builtin_amdgcn_s_setprio(0); } while (0)
; #define PG8_WAIT_V(n) asm volatile("s_waitcnt vmcnt(" #n ")" ::: "memory")
; #define PG8_WAIT_L(n) asm volatile("s_waitcnt lgkmcnt(" #n ")" ::: "memory")
; #define PG8_BAR __builtin_amdgcn_s_barrier()
; #define PG8_SCHED __builtin_amdgcn_sched_barrier(0)
; template <class Epi, class Sched, bool ALIGN_EPI = false, bool SP2 = false>
; __device__ __forceinline__ void gemm_phase(PG8_LAS unsigned char* lds, const Gemm g, const Sched& S, const Epi& E) {
;     ...
;             PG8_WAIT_V(8); PG8_WAIT_L(0); PG8_BAR; PG8_MMA(1, 0, At, B0); PG8_MMA(1, 1, At, B1); PG8_BAR; PG8_SCHED;
;             PG8_LDB(B0, 1, 0); PG8_LDB(B1, 1, 1); PG8_SCHED; PG8_LDA(At, 1, 0); PG8_STAGE(PG8_SA(0, 1), a2 + hstep, voffA);
;             PG8_WAIT_V(8); PG8_WAIT_L(0); PG8_BAR; PG8_MMA(0, 0, At, B0); PG8_MMA(0, 1, At, B1); PG8_BAR; PG8_SCHED;
	s_setprio 1
	s_waitcnt lgkmcnt(0)
	v_mfma_f32_16x16x32_bf16 v[60:63], v[152:155], v[188:191], v[60:63]
	v_mfma_f32_16x16x32_bf16 v[56:59], v[160:163], v[188:191], v[56:59]
	v_mfma_f32_16x16x32_bf16 v[44:47], v[160:163], v[196:199], v[44:47]
	v_mfma_f32_16x16x32_bf16 v[52:55], v[152:155], v[196:199], v[52:55]
	v_mfma_f32_16x16x32_bf16 v[36:39], v[152:155], v[204:207], v[36:39]
	v_mfma_f32_16x16x32_bf16 v[28:31], v[160:163], v[204:207], v[28:31]
	v_mfma_f32_16x16x32_bf16 v[12:15], v[160:163], v[212:215], v[12:15]
	v_mfma_f32_16x16x32_bf16 v[20:23], v[152:155], v[212:215], v[20:23]
	v_mfma_f32_16x16x32_bf16 v[20:23], v[156:159], v[216:219], v[20:23]
	v_mfma_f32_16x16x32_bf16 v[12:15], v[164:167], v[216:219], v[12:15]
	v_mfma_f32_16x16x32_bf16 v[28:31], v[164:167], v[208:211], v[28:31]
	v_mfma_f32_16x16x32_bf16 v[36:39], v[156:159], v[208:211], v[36:39]
	v_mfma_f32_16x16x32_bf16 v[52:55], v[156:159], v[200:203], v[52:55]
	v_mfma_f32_16x16x32_bf16 v[44:47], v[164:167], v[200:203], v[44:47]
	v_mfma_f32_16x16x32_bf16 v[56:59], v[164:167], v[192:195], v[56:59]
	v_mfma_f32_16x16x32_bf16 v[60:63], v[156:159], v[192:195], v[60:63]
	s_setprio 0
	s_setprio 1
	v_mfma_f32_16x16x32_bf16 v[48:51], v[168:171], v[188:191], v[48:51]
	v_mfma_f32_16x16x32_bf16 v[40:43], v[180:183], v[188:191], v[40:43]
	v_mfma_f32_16x16x32_bf16 v[24:27], v[180:183], v[196:199], v[24:27]
	v_mfma_f32_16x16x32_bf16 v[32:35], v[168:171], v[196:199], v[32:35]
	v_mfma_f32_16x16x32_bf16 v[16:19], v[168:171], v[204:207], v[16:19]
	v_mfma_f32_16x16x32_bf16 v[8:11], v[180:183], v[204:207], v[8:11]
	v_mfma_f32_16x16x32_bf16 v[0:3], v[180:183], v[212:215], v[0:3]
	v_mfma_f32_16x16x32_bf16 v[4:7], v[168:171], v[212:215], v[4:7]
	v_mfma_f32_16x16x32_bf16 v[4:7], v[172:175], v[216:219], v[4:7]
	v_mfma_f32_16x16x32_bf16 v[0:3], v[184:187], v[216:219], v[0:3]
	v_mfma_f32_16x16x32_bf16 v[8:11], v[184:187], v[208:211], v[8:11]
	v_mfma_f32_16x16x32_bf16 v[16:19], v[172:175], v[208:211], v[16:19]
	v_mfma_f32_16x16x32_bf16 v[32:35], v[172:175], v[200:203], v[32:35]
	v_mfma_f32_16x16x32_bf16 v[24:27], v[184:187], v[200:203], v[24:27]
	v_mfma_f32_16x16x32_bf16 v[40:43], v[184:187], v[192:195], v[40:43]
	v_mfma_f32_16x16x32_bf16 v[48:51], v[172:175], v[192:195], v[48:51]
	s_setprio 0
	s_barrier
	s_add_i32 s86, 0, 0x18000
	s_add_i32 s87, 0, 0x1c000
	v_add_u32_e32 v164, s86, v147
	v_add_u32_e32 v179, s87, v147
	ds_read_b128 v[152:155], v164
	ds_read_b128 v[156:159], v164 offset:1024
	ds_read_b128 v[160:163], v164 offset:2048
	ds_read_b128 v[164:167], v164 offset:3072
	ds_read_b128 v[168:171], v179
	ds_read_b128 v[172:175], v179 offset:1024
	ds_read_b128 v[180:183], v179 offset:2048
	ds_read_b128 v[184:187], v179 offset:3072
	s_add_u32 s30, s70, 0x80000
	s_addc_u32 s31, s71, 0
	s_mov_b32 m0, s46
	v_lshl_add_u64 v[224:225], s[30:31], 0, v[128:129]
	ds_read_b128 v[188:191], v151 offset:32768
	ds_read_b128 v[192:195], v151 offset:33792
	ds_read_b128 v[196:199], v151 offset:34816
	ds_read_b128 v[200:203], v151 offset:35840
	ds_read_b128 v[204:207], v151 offset:36864
	ds_read_b128 v[208:211], v151 offset:37888
	ds_read_b128 v[212:215], v151 offset:38912
	ds_read_b128 v[216:219], v151 offset:39936
	global_load_lds_dwordx4 v[224:225], off
	v_lshl_add_u64 v[224:225], s[30:31], 0, v[132:133]
	s_mov_b32 m0, s47
	s_nop 0
	global_load_lds_dwordx4 v[224:225], off
	s_waitcnt vmcnt(8)
	s_waitcnt lgkmcnt(0)
	s_barrier
	s_setprio 1
	s_waitcnt lgkmcnt(0)
	v_mfma_f32_16x16x32_bf16 v[124:127], v[152:155], v[188:191], v[124:127]
	v_mfma_f32_16x16x32_bf16 v[120:123], v[160:163], v[188:191], v[120:123]
	v_mfma_f32_16x16x32_bf16 v[108:111], v[160:163], v[196:199], v[108:111]
	v_mfma_f32_16x16x32_bf16 v[116:119], v[152:155], v[196:199], v[116:119]
	v_mfma_f32_16x16x32_bf16 v[100:103], v[152:155], v[204:207], v[100:103]
	v_mfma_f32_16x16x32_bf16 v[92:95], v[160:163], v[204:207], v[92:95]
	v_mfma_f32_16x16x32_bf16 v[76:79], v[160:163], v[212:215], v[76:79]
	v_mfma_f32_16x16x32_bf16 v[84:87], v[152:155], v[212:215], v[84:87]
	v_mfma_f32_16x16x32_bf16 v[84:87], v[156:159], v[216:219], v[84:87]
	v_mfma_f32_16x16x32_bf16 v[76:79], v[164:167], v[216:219], v[76:79]
	v_mfma_f32_16x16x32_bf16 v[92:95], v[164:167], v[208:211], v[92:95]
	v_mfma_f32_16x16x32_bf16 v[100:103], v[156:159], v[208:211], v[100:103]
	v_mfma_f32_16x16x32_bf16 v[116:119], v[156:159], v[200:203], v[116:119]
	v_mfma_f32_16x16x32_bf16 v[108:111], v[164:167], v[200:203], v[108:111]
	v_mfma_f32_16x16x32_bf16 v[120:123], v[164:167], v[192:195], v[120:123]
	v_mfma_f32_16x16x32_bf16 v[124:127], v[156:159], v[192:195], v[124:127]
	s_setprio 0
	s_setprio 1
	v_mfma_f32_16x16x32_bf16 v[112:115], v[168:171], v[188:191], v[112:115]
	v_mfma_f32_16x16x32_bf16 v[104:107], v[180:183], v[188:191], v[104:107]
	v_mfma_f32_16x16x32_bf16 v[88:91], v[180:183], v[196:199], v[88:91]
	v_mfma_f32_16x16x32_bf16 v[96:99], v[168:171], v[196:199], v[96:99]
	v_mfma_f32_16x16x32_bf16 v[80:83], v[168:171], v[204:207], v[80:83]
	v_mfma_f32_16x16x32_bf16 v[72:75], v[180:183], v[204:207], v[72:75]
	v_mfma_f32_16x16x32_bf16 v[64:67], v[180:183], v[212:215], v[64:67]
	v_mfma_f32_16x16x32_bf16 v[68:71], v[168:171], v[212:215], v[68:71]
	v_mfma_f32_16x16x32_bf16 v[68:71], v[172:175], v[216:219], v[68:71]
	v_mfma_f32_16x16x32_bf16 v[64:67], v[184:187], v[216:219], v[64:67]
	v_mfma_f32_16x16x32_bf16 v[72:75], v[184:187], v[208:211], v[72:75]
	v_mfma_f32_16x16x32_bf16 v[80:83], v[172:175], v[208:211], v[80:83]
	v_mfma_f32_16x16x32_bf16 v[96:99], v[172:175], v[200:203], v[96:99]
	v_mfma_f32_16x16x32_bf16 v[88:91], v[184:187], v[200:203], v[88:91]
	v_mfma_f32_16x16x32_bf16 v[104:107], v[184:187], v[192:195], v[104:107]
	v_mfma_f32_16x16x32_bf16 v[112:115], v[172:175], v[192:195], v[112:115]
	s_setprio 0
	s_barrier
; #define PG8_STAGE(bufoff, gbase, voff) do { _Pragma("unroll") for (int _i = 0; _i < 2; ++_i) \
;         __builtin_amdgcn_global_load_lds((const unsigned*)((const char*)(gbase) + (voff)[_i]), (PG8_LAS unsigned*)(lds + (bufoff) + ldsw + _i * 8192), 16, 0, 0); } while (0)
; #define PG8_LDA(dst, b, h) do { _Pragma("unroll") for (int m = 0; m < 4; ++m) _Pragma("unroll") for (int k = 0; k < 2; ++k) dst[m][k] = *(const PG8_LAS bf16x8*)(lds + PG8_SA(b, h) + aoff + m * 2048 + k * 1024); } while (0)
; #define PG8_MMA(ai, bj, At, Bt) do { __builtin_amdgcn_s_setprio(1); _Pragma("unroll") for (int m = 0; m < 4; ++m) _Pragma("unroll") for (int n = 0; n < 2; ++n) _Pragma("unroll") for (int k = 0; k < 2; ++k) \
;         acc[ai][bj][m][n] = __builtin_amdgcn_mfma_f32_16x16x32_bf16(Bt[n][k], At[m][k], acc[ai][bj][m][n], 0, 0, 0); __builtin_amdgcn_s_setprio(0); } while (0)
; #define PG8_WAIT_V(n) asm volatile("s_waitcnt vmcnt(" #n ")" ::: "memory")
; #define PG8_WAIT_L(n) asm volatile("s_waitcnt lgkmcnt(" #n ")" ::: "memory")
; #define PG8_BAR __builtin_amdgcn_s_barrier()
; #define PG8_SCHED __builtin_amdgcn_sched_barrier(0)
; template <class Epi, class Sched, bool ALIGN_EPI = false, bool SP2 = false>
; __device__ __forceinline__ void gemm_phase(PG8_LAS unsigned char* lds, const Gemm g, const Sched& S, const Epi& E) {
;     ...
;         for (int t = 0; t < nt; t += 2) {
;             const bool last = (t == nt - 2);
;             const char* a1 = cA + (size_t)(t + 1) * kstep;
;             const char* a2 = last ? nA : cA + (size_t)(t + 2) * kstep; const char* b2 = last ? nB : cB + (size_t)(t + 2) * kstep;
;     ...
;             PG8_LDA(At, 1, 1); PG8_STAGE(PG8_SB(1, 0), b3, voffB); PG8_STAGE(PG8_SB(1, 1), b3 + hstep, voffB); PG8_STAGE(PG8_SA(1, 0), a3, voffA);
;             PG8_WAIT_V(8); PG8_WAIT_L(0); PG8_BAR; PG8_MMA(1, 0, At, B0); PG8_MMA(1, 1, At, B1); PG8_BAR; PG8_SCHED;
	s_add_i32 s30, s86, s1
	v_lshl_add_u64 v[144:145], v[144:145], 0, s[8:9]
	s_mov_b32 m0, s30
	ds_read_b128 v[188:191], v151 offset:49152
	ds_read_b128 v[192:195], v151 offset:50176
	ds_read_b128 v[196:199], v151 offset:51200
	ds_read_b128 v[200:203], v151 offset:52224
	ds_read_b128 v[204:207], v151 offset:53248
	ds_read_b128 v[208:211], v151 offset:54272
	ds_read_b128 v[212:215], v151 offset:55296
	ds_read_b128 v[216:219], v151 offset:56320
	global_load_lds_dwordx4 v[144:145], off
	s_add_i32 m0, s30, 0x2000
	s_add_u32 s30, s68, 0x80080
	v_lshl_add_u64 v[144:145], v[176:177], 0, s[8:9]
	s_addc_u32 s31, s69, 0
	s_add_i32 s68, s87, s1
	global_load_lds_dwordx4 v[144:145], off
	v_lshl_add_u64 v[144:145], s[30:31], 0, v[130:131]
	s_mov_b32 m0, s68
	s_nop 0
	global_load_lds_dwordx4 v[144:145], off
	v_lshl_add_u64 v[144:145], s[30:31], 0, v[134:135]
	s_add_i32 m0, s68, 0x2000
	s_nop 0
	global_load_lds_dwordx4 v[144:145], off
	v_lshl_add_u64 v[144:145], v[220:221], 0, s[8:9]
	s_mov_b32 m0, s72
	s_nop 0
	global_load_lds_dwordx4 v[144:145], off
	v_lshl_add_u64 v[144:145], v[222:223], 0, s[8:9]
	s_mov_b32 m0, s73
	s_nop 0
	global_load_lds_dwordx4 v[144:145], off
	s_waitcnt vmcnt(8)
	s_waitcnt lgkmcnt(0)
	s_barrier
	s_setprio 1
	s_waitcnt lgkmcnt(0)
	v_mfma_f32_16x16x32_bf16 v[60:63], v[152:155], v[188:191], v[60:63]
	v_mfma_f32_16x16x32_bf16 v[56:59], v[160:163], v[188:191], v[56:59]
	v_mfma_f32_16x16x32_bf16 v[44:47], v[160:163], v[196:199], v[44:47]
	v_mfma_f32_16x16x32_bf16 v[52:55], v[152:155], v[196:199], v[52:55]
	v_mfma_f32_16x16x32_bf16 v[36:39], v[152:155], v[204:207], v[36:39]
	v_mfma_f32_16x16x32_bf16 v[28:31], v[160:163], v[204:207], v[28:31]
	v_mfma_f32_16x16x32_bf16 v[12:15], v[160:163], v[212:215], v[12:15]
	v_mfma_f32_16x16x32_bf16 v[20:23], v[152:155], v[212:215], v[20:23]
	v_mfma_f32_16x16x32_bf16 v[20:23], v[156:159], v[216:219], v[20:23]
	v_mfma_f32_16x16x32_bf16 v[12:15], v[164:167], v[216:219], v[12:15]
	v_mfma_f32_16x16x32_bf16 v[28:31], v[164:167], v[208:211], v[28:31]
	v_mfma_f32_16x16x32_bf16 v[36:39], v[156:159], v[208:211], v[36:39]
	v_mfma_f32_16x16x32_bf16 v[52:55], v[156:159], v[200:203], v[52:55]
	v_mfma_f32_16x16x32_bf16 v[44:47], v[164:167], v[200:203], v[44:47]
	v_mfma_f32_16x16x32_bf16 v[56:59], v[164:167], v[192:195], v[56:59]
	v_mfma_f32_16x16x32_bf16 v[60:63], v[156:159], v[192:195], v[60:63]
	s_setprio 0
	s_setprio 1
	v_mfma_f32_16x16x32_bf16 v[48:51], v[168:171], v[188:191], v[48:51]
	v_mfma_f32_16x16x32_bf16 v[40:43], v[180:183], v[188:191], v[40:43]
	v_mfma_f32_16x16x32_bf16 v[24:27], v[180:183], v[196:199], v[24:27]
	v_mfma_f32_16x16x32_bf16 v[32:35], v[168:171], v[196:199], v[32:35]
	v_mfma_f32_16x16x32_bf16 v[16:19], v[168:171], v[204:207], v[16:19]
	v_mfma_f32_16x16x32_bf16 v[8:11], v[180:183], v[204:207], v[8:11]
	v_mfma_f32_16x16x32_bf16 v[0:3], v[180:183], v[212:215], v[0:3]
	v_mfma_f32_16x16x32_bf16 v[4:7], v[168:171], v[212:215], v[4:7]
	v_mfma_f32_16x16x32_bf16 v[4:7], v[172:175], v[216:219], v[4:7]
	v_mfma_f32_16x16x32_bf16 v[0:3], v[184:187], v[216:219], v[0:3]
	v_mfma_f32_16x16x32_bf16 v[8:11], v[184:187], v[208:211], v[8:11]
	v_mfma_f32_16x16x32_bf16 v[16:19], v[172:175], v[208:211], v[16:19]
	v_mfma_f32_16x16x32_bf16 v[32:35], v[172:175], v[200:203], v[32:35]
	v_mfma_f32_16x16x32_bf16 v[24:27], v[184:187], v[200:203], v[24:27]
	v_mfma_f32_16x16x32_bf16 v[40:43], v[184:187], v[192:195], v[40:43]
	v_mfma_f32_16x16x32_bf16 v[48:51], v[172:175], v[192:195], v[48:51]
	s_setprio 0
	s_barrier
	s_add_i32 s85, s85, 2
	s_add_u32 s66, s66, 0x100
	s_addc_u32 s67, s67, 0
	s_add_u32 s83, s83, 0x100
	s_addc_u32 s84, s84, 0
	s_cmp_gt_u32 s85, 29
	s_cbranch_scc0 .LBB0_283
; __device__ __forceinline__ unsigned cvt_pk_bf16(float lo, float hi) { unsigned r; asm volatile("v_cvt_pk_bf16_f32 %0, %1, %2" : "=v"(r) : "v"(lo), "v"(hi)); return r; }
; #define PG8_WAIT_V(n) asm volatile("s_waitcnt vmcnt(" #n ")" ::: "memory")
; #define PG8_BAR __builtin_amdgcn_s_barrier()
;     __device__ __forceinline__ void operator()(const f32x4 (&acc)[2][2][4][2], const Unit& u, int wr, int wc, int fr, int fq) const {
;         const int row0 = u.pm * BM + wr * 64 + fr; const int col0 = u.pn * BM + wc * 32 + 8 * fq;
; #pragma unroll
;         for (int ai = 0; ai < 2; ++ai)
; #pragma unroll
;             for (int m = 0; m < 4; ++m) { bf16_t* rowp = O + (size_t)(row0 + ai * HALF + m * 16) * ldc + col0;
; #pragma unroll
;                 for (int bj = 0; bj < 2; ++bj) { const f32x4 v0 = acc[ai][bj][m][0], v1 = acc[ai][bj][m][1];
;                     u32x4 w; w.x = cvt_pk_bf16(v0[0], v0[1]); w.y = cvt_pk_bf16(v0[2], v0[3]); w.z = cvt_pk_bf16(v1[0], v1[1]); w.w = cvt_pk_bf16(v1[2], v1[3]);
;                     *(u32x4*)(rowp + bj * HALF) = w; } }
;     }
; template <class Epi, class Sched, bool ALIGN_EPI = false, bool SP2 = false>
; __device__ __forceinline__ void gemm_phase(PG8_LAS unsigned char* lds, const Gemm g, const Sched& S, const Epi& E) {
;     ...
;         if constexpr (!Epi::AFTER_DRAIN) { E(acc, cur, wr, wc, fr, fq); S.done(cur); }
;         if (!has_next) break;
; #pragma unroll
;         for (int a = 0; a < 2; ++a)
; #pragma unroll
;             for (int b = 0; b < 2; ++b)
; #pragma unroll
;                 for (int m = 0; m < 4; ++m)
; #pragma unroll
;                     for (int n = 0; n < 2; ++n) acc[a][b][m][n] = (f32x4){0.f, 0.f, 0.f, 0.f};
;         cur = nxt; cA = nA; cB = nB; ++ui;
;         if constexpr (ALIGN_EPI) { if (wr == 1) PG8_BAR; }
;     }
;     PG8_WAIT_V(0);
;     if constexpr (!ALIGN_EPI) { if (wr == 0) PG8_BAR; }
;     PG8_BAR;
	v_lshl_add_u32 v152, s64, 8, v146
	v_lshl_or_b32 v144, s80, 8, v148
	v_ashrrev_i32_e32 v153, 31, v152
	v_ashrrev_i32_e32 v145, 31, v144
	v_lshlrev_b64 v[154:155], 12, v[152:153]
	v_lshl_add_u64 v[154:155], s[18:19], 0, v[154:155]
	v_lshlrev_b64 v[156:157], 1, v[144:145]
	v_lshl_add_u64 v[144:145], v[154:155], 0, v[156:157]
	v_cvt_pk_bf16_f32 v124, v124, v125
	v_cvt_pk_bf16_f32 v125, v126, v127
	v_cvt_pk_bf16_f32 v126, v120, v121
	v_cvt_pk_bf16_f32 v127, v122, v123
	global_store_dwordx4 v[144:145], v[124:127], off
	v_cvt_pk_bf16_f32 v112, v112, v113
	v_cvt_pk_bf16_f32 v113, v114, v115
	v_cvt_pk_bf16_f32 v114, v104, v105
	v_or_b32_e32 v104, 16, v152
	v_ashrrev_i32_e32 v105, 31, v104
	v_lshlrev_b64 v[104:105], 12, v[104:105]
	v_lshl_add_u64 v[104:105], s[18:19], 0, v[104:105]
	v_cvt_pk_bf16_f32 v115, v106, v107
	global_store_dwordx4 v[144:145], v[112:115], off offset:256
	s_mov_b32 s80, s56
	s_mov_b32 s64, s58
	v_lshl_add_u64 v[112:113], v[104:105], 0, v[156:157]
	v_cvt_pk_bf16_f32 v104, v116, v117
	v_cvt_pk_bf16_f32 v105, v118, v119
	v_cvt_pk_bf16_f32 v106, v108, v109
	v_cvt_pk_bf16_f32 v107, v110, v111
	global_store_dwordx4 v[112:113], v[104:107], off
	v_cvt_pk_bf16_f32 v96, v96, v97
	v_cvt_pk_bf16_f32 v97, v98, v99
	v_cvt_pk_bf16_f32 v98, v88, v89
	v_or_b32_e32 v88, 32, v152
	v_ashrrev_i32_e32 v89, 31, v88
	v_lshlrev_b64 v[88:89], 12, v[88:89]
	v_lshl_add_u64 v[88:89], s[18:19], 0, v[88:89]
	v_cvt_pk_bf16_f32 v99, v90, v91
	global_store_dwordx4 v[112:113], v[96:99], off offset:256
	s_mov_b64 s[68:69], s[62:63]
	s_mov_b64 s[66:67], s[60:61]
	v_lshl_add_u64 v[96:97], v[88:89], 0, v[156:157]
	v_cvt_pk_bf16_f32 v88, v100, v101
	v_cvt_pk_bf16_f32 v89, v102, v103
	v_cvt_pk_bf16_f32 v90, v92, v93
	v_cvt_pk_bf16_f32 v91, v94, v95
	global_store_dwordx4 v[96:97], v[88:91], off
	v_cvt_pk_bf16_f32 v80, v80, v81
	v_cvt_pk_bf16_f32 v81, v82, v83
	v_cvt_pk_bf16_f32 v82, v72, v73
	v_or_b32_e32 v72, 48, v152
	v_ashrrev_i32_e32 v73, 31, v72
	v_lshlrev_b64 v[72:73], 12, v[72:73]
	v_lshl_add_u64 v[72:73], s[18:19], 0, v[72:73]
	v_cvt_pk_bf16_f32 v83, v74, v75
	global_store_dwordx4 v[96:97], v[80:83], off offset:256
	s_nop 1
	v_lshl_add_u64 v[80:81], v[72:73], 0, v[156:157]
	v_cvt_pk_bf16_f32 v72, v84, v85
	v_cvt_pk_bf16_f32 v73, v86, v87
	v_cvt_pk_bf16_f32 v74, v76, v77
	v_cvt_pk_bf16_f32 v75, v78, v79
	global_store_dwordx4 v[80:81], v[72:75], off
	v_cvt_pk_bf16_f32 v68, v68, v69
	v_cvt_pk_bf16_f32 v69, v70, v71
	v_cvt_pk_bf16_f32 v70, v64, v65
	v_cvt_pk_bf16_f32 v71, v66, v67
	global_store_dwordx4 v[80:81], v[68:71], off offset:256
	v_cvt_pk_bf16_f32 v60, v60, v61
	v_cvt_pk_bf16_f32 v61, v62, v63
	v_cvt_pk_bf16_f32 v62, v56, v57
	v_add_co_u32_e32 v56, vcc, s76, v144
	v_lshl_add_u64 v[64:65], v[144:145], 0, s[6:7]
	s_nop 0
	v_addc_co_u32_e32 v57, vcc, 0, v145, vcc
	v_cvt_pk_bf16_f32 v63, v58, v59
	global_store_dwordx4 v[56:57], v[60:63], off
	v_cvt_pk_bf16_f32 v48, v48, v49
	v_cvt_pk_bf16_f32 v49, v50, v51
	v_cvt_pk_bf16_f32 v50, v40, v41
	v_cvt_pk_bf16_f32 v51, v42, v43
	global_store_dwordx4 v[64:65], v[48:51], off offset:256
	v_cvt_pk_bf16_f32 v40, v52, v53
	v_cvt_pk_bf16_f32 v41, v54, v55
	v_cvt_pk_bf16_f32 v42, v44, v45
	v_add_co_u32_e32 v44, vcc, s77, v144
	s_nop 0
	v_lshl_add_u64 v[48:49], v[144:145], 0, s[10:11]
	v_addc_co_u32_e32 v45, vcc, 0, v145, vcc
	v_cvt_pk_bf16_f32 v43, v46, v47
	global_store_dwordx4 v[44:45], v[40:43], off
	v_cvt_pk_bf16_f32 v32, v32, v33
	v_cvt_pk_bf16_f32 v33, v34, v35
	v_cvt_pk_bf16_f32 v34, v24, v25
	v_cvt_pk_bf16_f32 v35, v26, v27
	global_store_dwordx4 v[48:49], v[32:35], off offset:256
	v_cvt_pk_bf16_f32 v24, v36, v37
	v_cvt_pk_bf16_f32 v25, v38, v39
	v_cvt_pk_bf16_f32 v26, v28, v29
	v_add_co_u32_e32 v28, vcc, s78, v144
	s_nop 0
	v_lshl_add_u64 v[32:33], v[144:145], 0, s[36:37]
	v_addc_co_u32_e32 v29, vcc, 0, v145, vcc
	v_cvt_pk_bf16_f32 v27, v30, v31
	global_store_dwordx4 v[28:29], v[24:27], off
	v_cvt_pk_bf16_f32 v16, v16, v17
	v_cvt_pk_bf16_f32 v17, v18, v19
	v_cvt_pk_bf16_f32 v18, v8, v9
	v_cvt_pk_bf16_f32 v19, v10, v11
	global_store_dwordx4 v[32:33], v[16:19], off offset:256
	v_cvt_pk_bf16_f32 v8, v20, v21
	v_cvt_pk_bf16_f32 v9, v22, v23
	v_cvt_pk_bf16_f32 v10, v12, v13
	v_add_co_u32_e32 v12, vcc, s79, v144
	s_nop 0
	v_lshl_add_u64 v[16:17], v[144:145], 0, s[54:55]
	v_addc_co_u32_e32 v13, vcc, 0, v145, vcc
	s_and_b64 vcc, exec, s[4:5]
	v_cvt_pk_bf16_f32 v11, v14, v15
	global_store_dwordx4 v[12:13], v[8:11], off
	v_cvt_pk_bf16_f32 v4, v4, v5
	v_cvt_pk_bf16_f32 v5, v6, v7
	v_cvt_pk_bf16_f32 v6, v0, v1
	v_cvt_pk_bf16_f32 v7, v2, v3
	global_store_dwordx4 v[16:17], v[4:7], off offset:256
	s_cbranch_vccz .LBB0_276
	s_waitcnt vmcnt(0)
	s_cmpk_gt_u32 s0, 0xff
	s_cbranch_scc1 .LBB0_287
	s_barrier

; #define PG8_STAGE(bufoff, gbase, voff) do { _Pragma("unroll") for (int _i = 0; _i < 2; ++_i) \
;         __builtin_amdgcn_global_load_lds((const unsigned*)((const char*)(gbase) + (voff)[_i]), (PG8_LAS unsigned*)(lds + (bufoff) + ldsw + _i * 8192), 16, 0, 0); } while (0)
; #define PG8_LDA(dst, b, h) do { _Pragma("unroll") for (int m = 0; m < 4; ++m) _Pragma("unroll") for (int k = 0; k < 2; ++k) dst[m][k] = *(const PG8_LAS bf16x8*)(lds + PG8_SA(b, h) + aoff + m * 2048 + k * 1024); } while (0)
; #define PG8_LDB(dst, b, h) do { _Pragma("unroll") for (int n = 0; n < 2; ++n) _Pragma("unroll") for (int k = 0; k < 2; ++k) dst[n][k] = *(const PG8_LAS bf16x8*)(lds + PG8_SB(b, h) + boff + n * 2048 + k * 1024); } while (0)
; #define PG8_MMA(ai, bj, At, Bt) do { __builtin_amdgcn_s_setprio(1); _Pragma("unroll") for (int m = 0; m < 4; ++m) _Pragma("unroll") for (int n = 0; n < 2; ++n) _Pragma("unroll") for (int k = 0; k < 2; ++k) \
;         acc[ai][bj][m][n] = __builtin_amdgcn_mfma_f32_16x16x32_bf16(Bt[n][k], At[m][k], acc[ai][bj][m][n], 0, 0, 0); __builtin_amdgcn_s_setprio(0); } while (0)
; #define PG8_WAIT_V(n) asm volatile("s_waitcnt vmcnt(" #n ")" ::: "memory")
; #define PG8_WAIT_L(n) asm volatile("s_waitcnt lgkmcnt(" #n ")" ::: "memory")
; #define PG8_BAR __builtin_amdgcn_s_barrier()
; #define PG8_SCHED __builtin_amdgcn_sched_barrier(0)
; template <class Epi, class Sched, bool ALIGN_EPI = false, bool SP2 = false>
; __device__ __forceinline__ void gemm_phase(PG8_LAS unsigned char* lds, const Gemm g, const Sched& S, const Epi& E) {
;     ...
;             const bool last = (t == nt - 2);
;             const char* a1 = cA + (size_t)(t + 1) * kstep;
;             const char* a2 = last ? nA : cA + (size_t)(t + 2) * kstep; const char* b2 = last ? nB : cB + (size_t)(t + 2) * kstep;
;             const char* a3 = a2 + kstep; const char* b3 = b2 + kstep;
;             if (last && has_next) S.a_ready(nxt);
;             if constexpr (SP2) {
;             PG8_LDB(B0, 0, 0); PG8_LDB(B1, 0, 1); PG8_SCHED; PG8_LDA(At, 0, 0); PG8_STAGE(PG8_SA(1, 1), a1 + hstep, voffA);
;             PG8_WAIT_V(8); PG8_WAIT_L(0); PG8_BAR; PG8_MMA(0, 0, At, B0); PG8_MMA(0, 1, At, B1); PG8_BAR; PG8_SCHED;
;             PG8_LDA(At, 0, 1); PG8_STAGE(PG8_SB(0, 0), b2, voffB); PG8_STAGE(PG8_SB(0, 1), b2 + hstep, voffB); PG8_STAGE(PG8_SA(0, 0), a2, voffA);
.LBB0_404:
	ds_read_b128 v[118:121], v217
	ds_read_b128 v[126:129], v217 offset:1024
	ds_read_b128 v[130:133], v217 offset:2048
	ds_read_b128 v[134:137], v217 offset:3072
	ds_read_b128 v[138:141], v218
	ds_read_b128 v[142:145], v218 offset:1024
	ds_read_b128 v[146:149], v218 offset:2048
	ds_read_b128 v[150:153], v218 offset:3072
	s_add_u32 s30, s10, 0xfff80080
	s_addc_u32 s31, s11, -1
	s_cmp_eq_u32 s65, 28
	s_cselect_b32 s75, s1, s31
	s_cselect_b32 s74, s22, s30
	s_cselect_b32 s73, s33, s63
	s_cselect_b32 s72, s46, s47
	v_lshl_add_u64 v[112:113], s[10:11], 0, v[196:197]
	s_add_i32 m0, s77, 0xc000
	ds_read_b128 v[154:157], v219
	ds_read_b128 v[166:169], v219 offset:1024
	ds_read_b128 v[170:173], v219 offset:2048
	ds_read_b128 v[174:177], v219 offset:3072
	ds_read_b128 v[204:207], v219 offset:4096
	ds_read_b128 v[208:211], v219 offset:5120
	ds_read_b128 v[226:229], v219 offset:6144
	ds_read_b128 v[230:233], v219 offset:7168
	global_load_lds_dwordx4 v[112:113], off
	v_lshl_add_u64 v[112:113], s[10:11], 0, v[198:199]
	s_add_i32 m0, s77, 0xe000
	s_nop 0
	global_load_lds_dwordx4 v[112:113], off
	s_waitcnt vmcnt(8)
	s_waitcnt lgkmcnt(0)
	s_barrier
	s_setprio 1
	s_waitcnt lgkmcnt(0)
	v_mfma_f32_16x16x32_bf16 v[162:165], v[118:121], v[154:157], v[162:165]
	v_mfma_f32_16x16x32_bf16 v[60:63], v[130:133], v[154:157], v[60:63]
	v_mfma_f32_16x16x32_bf16 v[52:55], v[130:133], v[170:173], v[52:55]
	v_mfma_f32_16x16x32_bf16 v[122:125], v[118:121], v[170:173], v[122:125]
	v_mfma_f32_16x16x32_bf16 v[108:111], v[118:121], v[204:207], v[108:111]
	v_mfma_f32_16x16x32_bf16 v[44:47], v[130:133], v[204:207], v[44:47]
	v_mfma_f32_16x16x32_bf16 v[40:43], v[130:133], v[226:229], v[40:43]
	v_mfma_f32_16x16x32_bf16 v[104:107], v[118:121], v[226:229], v[104:107]
	v_mfma_f32_16x16x32_bf16 v[104:107], v[126:129], v[230:233], v[104:107]
	v_mfma_f32_16x16x32_bf16 v[40:43], v[134:137], v[230:233], v[40:43]
	v_mfma_f32_16x16x32_bf16 v[44:47], v[134:137], v[208:211], v[44:47]
	v_mfma_f32_16x16x32_bf16 v[108:111], v[126:129], v[208:211], v[108:111]
	v_mfma_f32_16x16x32_bf16 v[122:125], v[126:129], v[174:177], v[122:125]
	v_mfma_f32_16x16x32_bf16 v[52:55], v[134:137], v[174:177], v[52:55]
	v_mfma_f32_16x16x32_bf16 v[60:63], v[134:137], v[166:169], v[60:63]
	v_mfma_f32_16x16x32_bf16 v[162:165], v[126:129], v[166:169], v[162:165]
	s_setprio 0
	s_setprio 1
	v_mfma_f32_16x16x32_bf16 v[158:161], v[138:141], v[154:157], v[158:161]
	v_mfma_f32_16x16x32_bf16 v[56:59], v[146:149], v[154:157], v[56:59]
	v_mfma_f32_16x16x32_bf16 v[48:51], v[146:149], v[170:173], v[48:51]
	v_mfma_f32_16x16x32_bf16 v[112:115], v[138:141], v[170:173], v[114:117]
	v_mfma_f32_16x16x32_bf16 v[100:103], v[138:141], v[204:207], v[100:103]
	v_mfma_f32_16x16x32_bf16 v[36:39], v[146:149], v[204:207], v[36:39]
	v_mfma_f32_16x16x32_bf16 v[32:35], v[146:149], v[226:229], v[32:35]
	v_mfma_f32_16x16x32_bf16 v[96:99], v[138:141], v[226:229], v[96:99]
	v_mfma_f32_16x16x32_bf16 v[96:99], v[142:145], v[230:233], v[96:99]
	v_mfma_f32_16x16x32_bf16 v[32:35], v[150:153], v[230:233], v[32:35]
	v_mfma_f32_16x16x32_bf16 v[36:39], v[150:153], v[208:211], v[36:39]
	v_mfma_f32_16x16x32_bf16 v[100:103], v[142:145], v[208:211], v[100:103]
	v_mfma_f32_16x16x32_bf16 v[112:115], v[142:145], v[174:177], v[112:115]
	v_mfma_f32_16x16x32_bf16 v[48:51], v[150:153], v[174:177], v[48:51]
	v_mfma_f32_16x16x32_bf16 v[56:59], v[150:153], v[166:169], v[56:59]
	v_mfma_f32_16x16x32_bf16 v[158:161], v[142:145], v[166:169], v[158:161]
	s_setprio 0
	s_barrier
	s_add_i32 s30, s85, s29
	v_lshl_add_u64 v[234:235], s[72:73], 0, v[184:185]
	s_mov_b32 m0, s30
	ds_read_b128 v[154:157], v219 offset:16384
	ds_read_b128 v[166:169], v219 offset:17408
	ds_read_b128 v[170:173], v219 offset:18432
	ds_read_b128 v[174:177], v219 offset:19456
	ds_read_b128 v[204:207], v219 offset:20480
	ds_read_b128 v[208:211], v219 offset:21504
	ds_read_b128 v[226:229], v219 offset:22528
	ds_read_b128 v[230:233], v219 offset:23552
	global_load_lds_dwordx4 v[234:235], off
	s_add_i32 m0, s30, 0x2000
	s_add_u32 s30, s72, 0x80000
	v_lshl_add_u64 v[236:237], s[72:73], 0, v[180:181]
	s_addc_u32 s31, s73, 0
	s_add_i32 s71, s86, s29
	global_load_lds_dwordx4 v[236:237], off
	v_lshl_add_u64 v[116:117], s[30:31], 0, v[184:185]
	s_mov_b32 m0, s71
	v_lshl_add_u64 v[238:239], s[74:75], 0, v[186:187]
	global_load_lds_dwordx4 v[116:117], off
	v_lshl_add_u64 v[116:117], s[30:31], 0, v[180:181]
	s_add_i32 m0, s71, 0x2000
	v_lshl_add_u64 v[240:241], s[74:75], 0, v[182:183]
	global_load_lds_dwordx4 v[116:117], off
	s_mov_b32 m0, s77
	s_nop 0
	global_load_lds_dwordx4 v[238:239], off
	s_mov_b32 m0, s78
	s_nop 0
	global_load_lds_dwordx4 v[240:241], off
	s_waitcnt vmcnt(8)
	s_waitcnt lgkmcnt(0)
	s_barrier
; #define PG8_STAGE(bufoff, gbase, voff) do { _Pragma("unroll") for (int _i = 0; _i < 2; ++_i) \
;         __builtin_amdgcn_global_load_lds((const unsigned*)((const char*)(gbase) + (voff)[_i]), (PG8_LAS unsigned*)(lds + (bufoff) + ldsw + _i * 8192), 16, 0, 0); } while (0)
; #define PG8_LDA(dst, b, h) do { _Pragma("unroll") for (int m = 0; m < 4; ++m) _Pragma("unroll") for (int k = 0; k < 2; ++k) dst[m][k] = *(const PG8_LAS bf16x8*)(lds + PG8_SA(b, h) + aoff + m * 2048 + k * 1024); } while (0)
; #define PG8_LDB(dst, b, h) do { _Pragma("unroll") for (int n = 0; n < 2; ++n) _Pragma("unroll") for (int k = 0; k < 2; ++k) dst[n][k] = *(const PG8_LAS bf16x8*)(lds + PG8_SB(b, h) + boff + n * 2048 + k * 1024); } while (0)
; #define PG8_MMA(ai, bj, At, Bt) do { __builtin_amdgcn_s_setprio(1); _Pragma("unroll") for (int m = 0; m < 4; ++m) _Pragma("unroll") for (int n = 0; n < 2; ++n) _Pragma("unroll") for (int k = 0; k < 2; ++k) \
;         acc[ai][bj][m][n] = __builtin_amdgcn_mfma_f32_16x16x32_bf16(Bt[n][k], At[m][k], acc[ai][bj][m][n], 0, 0, 0); __builtin_amdgcn_s_setprio(0); } while (0)
; #define PG8_WAIT_V(n) asm volatile("s_waitcnt vmcnt(" #n ")" ::: "memory")
; #define PG8_WAIT_L(n) asm volatile("s_waitcnt lgkmcnt(" #n ")" ::: "memory")
; #define PG8_BAR __builtin_amdgcn_s_barrier()
; #define PG8_SCHED __builtin_amdgcn_sched_barrier(0)
; template <class Epi, class Sched, bool ALIGN_EPI = false, bool SP2 = false>
; __device__ __forceinline__ void gemm_phase(PG8_LAS unsigned char* lds, const Gemm g, const Sched& S, const Epi& E) {
;     ...
;             PG8_WAIT_V(8); PG8_WAIT_L(0); PG8_BAR; PG8_MMA(1, 0, At, B0); PG8_MMA(1, 1, At, B1); PG8_BAR; PG8_SCHED;
;             PG8_LDB(B0, 1, 0); PG8_LDB(B1, 1, 1); PG8_SCHED; PG8_LDA(At, 1, 0); PG8_STAGE(PG8_SA(0, 1), a2 + hstep, voffA);
;             PG8_WAIT_V(8); PG8_WAIT_L(0); PG8_BAR; PG8_MMA(0, 0, At, B0); PG8_MMA(0, 1, At, B1); PG8_BAR; PG8_SCHED;
	s_setprio 1
	s_waitcnt lgkmcnt(0)
	v_mfma_f32_16x16x32_bf16 v[92:95], v[118:121], v[154:157], v[92:95]
	v_mfma_f32_16x16x32_bf16 v[28:31], v[130:133], v[154:157], v[28:31]
	v_mfma_f32_16x16x32_bf16 v[20:23], v[130:133], v[170:173], v[20:23]
	v_mfma_f32_16x16x32_bf16 v[84:87], v[118:121], v[170:173], v[84:87]
	v_mfma_f32_16x16x32_bf16 v[76:79], v[118:121], v[204:207], v[76:79]
	v_mfma_f32_16x16x32_bf16 v[12:15], v[130:133], v[204:207], v[12:15]
	v_mfma_f32_16x16x32_bf16 v[8:11], v[130:133], v[226:229], v[8:11]
	v_mfma_f32_16x16x32_bf16 v[72:75], v[118:121], v[226:229], v[72:75]
	v_mfma_f32_16x16x32_bf16 v[72:75], v[126:129], v[230:233], v[72:75]
	v_mfma_f32_16x16x32_bf16 v[8:11], v[134:137], v[230:233], v[8:11]
	v_mfma_f32_16x16x32_bf16 v[12:15], v[134:137], v[208:211], v[12:15]
	v_mfma_f32_16x16x32_bf16 v[76:79], v[126:129], v[208:211], v[76:79]
	v_mfma_f32_16x16x32_bf16 v[84:87], v[126:129], v[174:177], v[84:87]
	v_mfma_f32_16x16x32_bf16 v[20:23], v[134:137], v[174:177], v[20:23]
	v_mfma_f32_16x16x32_bf16 v[28:31], v[134:137], v[166:169], v[28:31]
	v_mfma_f32_16x16x32_bf16 v[92:95], v[126:129], v[166:169], v[92:95]
	s_setprio 0
	s_setprio 1
	v_mfma_f32_16x16x32_bf16 v[88:91], v[138:141], v[154:157], v[88:91]
	v_mfma_f32_16x16x32_bf16 v[24:27], v[146:149], v[154:157], v[24:27]
	v_mfma_f32_16x16x32_bf16 v[16:19], v[146:149], v[170:173], v[16:19]
	v_mfma_f32_16x16x32_bf16 v[80:83], v[138:141], v[170:173], v[80:83]
	v_mfma_f32_16x16x32_bf16 v[68:71], v[138:141], v[204:207], v[68:71]
	v_mfma_f32_16x16x32_bf16 v[4:7], v[146:149], v[204:207], v[4:7]
	v_mfma_f32_16x16x32_bf16 v[0:3], v[146:149], v[226:229], v[0:3]
	v_mfma_f32_16x16x32_bf16 v[64:67], v[138:141], v[226:229], v[64:67]
	v_mfma_f32_16x16x32_bf16 v[64:67], v[142:145], v[230:233], v[64:67]
	v_mfma_f32_16x16x32_bf16 v[0:3], v[150:153], v[230:233], v[0:3]
	v_mfma_f32_16x16x32_bf16 v[4:7], v[150:153], v[208:211], v[4:7]
	v_mfma_f32_16x16x32_bf16 v[68:71], v[142:145], v[208:211], v[68:71]
	v_mfma_f32_16x16x32_bf16 v[80:83], v[142:145], v[174:177], v[80:83]
	v_mfma_f32_16x16x32_bf16 v[16:19], v[150:153], v[174:177], v[16:19]
	v_mfma_f32_16x16x32_bf16 v[24:27], v[150:153], v[166:169], v[24:27]
	v_mfma_f32_16x16x32_bf16 v[88:91], v[142:145], v[166:169], v[88:91]
	s_setprio 0
	s_barrier
	s_add_i32 s71, 0, 0x18000
	v_add_u32_e32 v116, s71, v213
	s_add_i32 s88, 0, 0x1c000
	ds_read_b128 v[118:121], v116
	ds_read_b128 v[126:129], v116 offset:1024
	ds_read_b128 v[130:133], v116 offset:2048
	ds_read_b128 v[134:137], v116 offset:3072
	v_add_u32_e32 v116, s88, v213
	ds_read_b128 v[138:141], v116
	ds_read_b128 v[142:145], v116 offset:1024
	ds_read_b128 v[146:149], v116 offset:2048
	ds_read_b128 v[150:153], v116 offset:3072
	s_add_u32 s30, s74, 0x80000
	s_addc_u32 s31, s75, 0
	s_mov_b32 m0, s79
	v_lshl_add_u64 v[116:117], s[30:31], 0, v[186:187]
	ds_read_b128 v[154:157], v219 offset:32768
	ds_read_b128 v[166:169], v219 offset:33792
	ds_read_b128 v[170:173], v219 offset:34816
	ds_read_b128 v[174:177], v219 offset:35840
	ds_read_b128 v[204:207], v219 offset:36864
	ds_read_b128 v[208:211], v219 offset:37888
	ds_read_b128 v[226:229], v219 offset:38912
	ds_read_b128 v[230:233], v219 offset:39936
	global_load_lds_dwordx4 v[116:117], off
	v_lshl_add_u64 v[116:117], s[30:31], 0, v[182:183]
	s_mov_b32 m0, s80
	s_nop 0
	global_load_lds_dwordx4 v[116:117], off
	s_waitcnt vmcnt(8)
	s_waitcnt lgkmcnt(0)
	s_barrier
	s_setprio 1
	s_waitcnt lgkmcnt(0)
	v_mfma_f32_16x16x32_bf16 v[162:165], v[118:121], v[154:157], v[162:165]
	v_mfma_f32_16x16x32_bf16 v[60:63], v[130:133], v[154:157], v[60:63]
	v_mfma_f32_16x16x32_bf16 v[52:55], v[130:133], v[170:173], v[52:55]
	v_mfma_f32_16x16x32_bf16 v[122:125], v[118:121], v[170:173], v[122:125]
	v_mfma_f32_16x16x32_bf16 v[108:111], v[118:121], v[204:207], v[108:111]
	v_mfma_f32_16x16x32_bf16 v[44:47], v[130:133], v[204:207], v[44:47]
	v_mfma_f32_16x16x32_bf16 v[40:43], v[130:133], v[226:229], v[40:43]
	v_mfma_f32_16x16x32_bf16 v[104:107], v[118:121], v[226:229], v[104:107]
	v_mfma_f32_16x16x32_bf16 v[104:107], v[126:129], v[230:233], v[104:107]
	v_mfma_f32_16x16x32_bf16 v[40:43], v[134:137], v[230:233], v[40:43]
	v_mfma_f32_16x16x32_bf16 v[44:47], v[134:137], v[208:211], v[44:47]
	v_mfma_f32_16x16x32_bf16 v[108:111], v[126:129], v[208:211], v[108:111]
	v_mfma_f32_16x16x32_bf16 v[122:125], v[126:129], v[174:177], v[122:125]
	v_mfma_f32_16x16x32_bf16 v[52:55], v[134:137], v[174:177], v[52:55]
	v_mfma_f32_16x16x32_bf16 v[60:63], v[134:137], v[166:169], v[60:63]
	v_mfma_f32_16x16x32_bf16 v[162:165], v[126:129], v[166:169], v[162:165]
	s_setprio 0
	s_setprio 1
	v_mfma_f32_16x16x32_bf16 v[158:161], v[138:141], v[154:157], v[158:161]
	v_mfma_f32_16x16x32_bf16 v[56:59], v[146:149], v[154:157], v[56:59]
	v_mfma_f32_16x16x32_bf16 v[48:51], v[146:149], v[170:173], v[48:51]
	v_mfma_f32_16x16x32_bf16 v[112:115], v[138:141], v[170:173], v[112:115]
	v_mfma_f32_16x16x32_bf16 v[100:103], v[138:141], v[204:207], v[100:103]
	v_mfma_f32_16x16x32_bf16 v[36:39], v[146:149], v[204:207], v[36:39]
	v_mfma_f32_16x16x32_bf16 v[32:35], v[146:149], v[226:229], v[32:35]
	v_mfma_f32_16x16x32_bf16 v[96:99], v[138:141], v[226:229], v[96:99]
	v_mfma_f32_16x16x32_bf16 v[96:99], v[142:145], v[230:233], v[96:99]
	v_mfma_f32_16x16x32_bf16 v[32:35], v[150:153], v[230:233], v[32:35]
	v_mfma_f32_16x16x32_bf16 v[36:39], v[150:153], v[208:211], v[36:39]
	v_mfma_f32_16x16x32_bf16 v[100:103], v[142:145], v[208:211], v[100:103]
	v_mfma_f32_16x16x32_bf16 v[114:117], v[142:145], v[174:177], v[112:115]
	v_mfma_f32_16x16x32_bf16 v[48:51], v[150:153], v[174:177], v[48:51]
	v_mfma_f32_16x16x32_bf16 v[56:59], v[150:153], v[166:169], v[56:59]
	v_mfma_f32_16x16x32_bf16 v[158:161], v[142:145], v[166:169], v[158:161]
	s_setprio 0
	s_barrier
; #define PG8_STAGE(bufoff, gbase, voff) do { _Pragma("unroll") for (int _i = 0; _i < 2; ++_i) \
;         __builtin_amdgcn_global_load_lds((const unsigned*)((const char*)(gbase) + (voff)[_i]), (PG8_LAS unsigned*)(lds + (bufoff) + ldsw + _i * 8192), 16, 0, 0); } while (0)
; #define PG8_LDA(dst, b, h) do { _Pragma("unroll") for (int m = 0; m < 4; ++m) _Pragma("unroll") for (int k = 0; k < 2; ++k) dst[m][k] = *(const PG8_LAS bf16x8*)(lds + PG8_SA(b, h) + aoff + m * 2048 + k * 1024); } while (0)
; #define PG8_MMA(ai, bj, At, Bt) do { __builtin_amdgcn_s_setprio(1); _Pragma("unroll") for (int m = 0; m < 4; ++m) _Pragma("unroll") for (int n = 0; n < 2; ++n) _Pragma("unroll") for (int k = 0; k < 2; ++k) \
;         acc[ai][bj][m][n] = __builtin_amdgcn_mfma_f32_16x16x32_bf16(Bt[n][k], At[m][k], acc[ai][bj][m][n], 0, 0, 0); __builtin_amdgcn_s_setprio(0); } while (0)
; #define PG8_WAIT_V(n) asm volatile("s_waitcnt vmcnt(" #n ")" ::: "memory")
; #define PG8_WAIT_L(n) asm volatile("s_waitcnt lgkmcnt(" #n ")" ::: "memory")
; #define PG8_BAR __builtin_amdgcn_s_barrier()
; #define PG8_SCHED __builtin_amdgcn_sched_barrier(0)
; template <class Epi, class Sched, bool ALIGN_EPI = false, bool SP2 = false>
; __device__ __forceinline__ void gemm_phase(PG8_LAS unsigned char* lds, const Gemm g, const Sched& S, const Epi& E) {
;     ...
;         for (int t = 0; t < nt; t += 2) {
;             const bool last = (t == nt - 2);
;             const char* a1 = cA + (size_t)(t + 1) * kstep;
;             const char* a2 = last ? nA : cA + (size_t)(t + 2) * kstep; const char* b2 = last ? nB : cB + (size_t)(t + 2) * kstep;
;     ...
;             PG8_LDA(At, 1, 1); PG8_STAGE(PG8_SB(1, 0), b3, voffB); PG8_STAGE(PG8_SB(1, 1), b3 + hstep, voffB); PG8_STAGE(PG8_SA(1, 0), a3, voffA);
;             PG8_WAIT_V(8); PG8_WAIT_L(0); PG8_BAR; PG8_MMA(1, 0, At, B0); PG8_MMA(1, 1, At, B1); PG8_BAR; PG8_SCHED;
	s_add_i32 s30, s71, s29
	v_lshl_add_u64 v[112:113], v[234:235], 0, s[52:53]
	s_mov_b32 m0, s30
	ds_read_b128 v[154:157], v219 offset:49152
	ds_read_b128 v[166:169], v219 offset:50176
	ds_read_b128 v[170:173], v219 offset:51200
	ds_read_b128 v[174:177], v219 offset:52224
	ds_read_b128 v[204:207], v219 offset:53248
	ds_read_b128 v[208:211], v219 offset:54272
	ds_read_b128 v[226:229], v219 offset:55296
	ds_read_b128 v[230:233], v219 offset:56320
	global_load_lds_dwordx4 v[112:113], off
	s_add_i32 m0, s30, 0x2000
	s_add_u32 s30, s72, 0x80080
	v_lshl_add_u64 v[112:113], v[236:237], 0, s[52:53]
	s_addc_u32 s31, s73, 0
	s_add_i32 s71, s88, s29
	global_load_lds_dwordx4 v[112:113], off
	v_lshl_add_u64 v[112:113], s[30:31], 0, v[184:185]
	s_mov_b32 m0, s71
	s_nop 0
	global_load_lds_dwordx4 v[112:113], off
	v_lshl_add_u64 v[112:113], s[30:31], 0, v[180:181]
	s_add_i32 m0, s71, 0x2000
	s_nop 0
	global_load_lds_dwordx4 v[112:113], off
	v_lshl_add_u64 v[112:113], v[238:239], 0, s[52:53]
	s_mov_b32 m0, s83
	s_nop 0
	global_load_lds_dwordx4 v[112:113], off
	v_lshl_add_u64 v[112:113], v[240:241], 0, s[52:53]
	s_mov_b32 m0, s84
	s_nop 0
	global_load_lds_dwordx4 v[112:113], off
	s_waitcnt vmcnt(8)
	s_waitcnt lgkmcnt(0)
	s_barrier
	s_setprio 1
	s_waitcnt lgkmcnt(0)
	v_mfma_f32_16x16x32_bf16 v[92:95], v[118:121], v[154:157], v[92:95]
	v_mfma_f32_16x16x32_bf16 v[28:31], v[130:133], v[154:157], v[28:31]
	v_mfma_f32_16x16x32_bf16 v[20:23], v[130:133], v[170:173], v[20:23]
	v_mfma_f32_16x16x32_bf16 v[84:87], v[118:121], v[170:173], v[84:87]
	v_mfma_f32_16x16x32_bf16 v[76:79], v[118:121], v[204:207], v[76:79]
	v_mfma_f32_16x16x32_bf16 v[12:15], v[130:133], v[204:207], v[12:15]
	v_mfma_f32_16x16x32_bf16 v[8:11], v[130:133], v[226:229], v[8:11]
	v_mfma_f32_16x16x32_bf16 v[72:75], v[118:121], v[226:229], v[72:75]
	v_mfma_f32_16x16x32_bf16 v[72:75], v[126:129], v[230:233], v[72:75]
	v_mfma_f32_16x16x32_bf16 v[8:11], v[134:137], v[230:233], v[8:11]
	v_mfma_f32_16x16x32_bf16 v[12:15], v[134:137], v[208:211], v[12:15]
	v_mfma_f32_16x16x32_bf16 v[76:79], v[126:129], v[208:211], v[76:79]
	v_mfma_f32_16x16x32_bf16 v[84:87], v[126:129], v[174:177], v[84:87]
	v_mfma_f32_16x16x32_bf16 v[20:23], v[134:137], v[174:177], v[20:23]
	v_mfma_f32_16x16x32_bf16 v[28:31], v[134:137], v[166:169], v[28:31]
	v_mfma_f32_16x16x32_bf16 v[92:95], v[126:129], v[166:169], v[92:95]
	s_setprio 0
	s_setprio 1
	v_mfma_f32_16x16x32_bf16 v[88:91], v[138:141], v[154:157], v[88:91]
	v_mfma_f32_16x16x32_bf16 v[24:27], v[146:149], v[154:157], v[24:27]
	v_mfma_f32_16x16x32_bf16 v[16:19], v[146:149], v[170:173], v[16:19]
	v_mfma_f32_16x16x32_bf16 v[80:83], v[138:141], v[170:173], v[80:83]
	v_mfma_f32_16x16x32_bf16 v[68:71], v[138:141], v[204:207], v[68:71]
	v_mfma_f32_16x16x32_bf16 v[4:7], v[146:149], v[204:207], v[4:7]
	v_mfma_f32_16x16x32_bf16 v[0:3], v[146:149], v[226:229], v[0:3]
	v_mfma_f32_16x16x32_bf16 v[64:67], v[138:141], v[226:229], v[64:67]
	v_mfma_f32_16x16x32_bf16 v[64:67], v[142:145], v[230:233], v[64:67]
	v_mfma_f32_16x16x32_bf16 v[0:3], v[150:153], v[230:233], v[0:3]
	v_mfma_f32_16x16x32_bf16 v[4:7], v[150:153], v[208:211], v[4:7]
	v_mfma_f32_16x16x32_bf16 v[68:71], v[142:145], v[208:211], v[68:71]
	v_mfma_f32_16x16x32_bf16 v[80:83], v[142:145], v[174:177], v[80:83]
	v_mfma_f32_16x16x32_bf16 v[16:19], v[150:153], v[174:177], v[16:19]
	v_mfma_f32_16x16x32_bf16 v[24:27], v[150:153], v[166:169], v[24:27]
	v_mfma_f32_16x16x32_bf16 v[88:91], v[142:145], v[166:169], v[88:91]
	s_setprio 0
	s_barrier
	s_add_i32 s65, s65, 2
	s_add_u32 s10, s10, 0x100
	s_addc_u32 s11, s11, 0
	s_add_u32 s47, s47, 0x100
	s_addc_u32 s63, s63, 0
	s_cmp_gt_u32 s65, 29
	s_cbranch_scc0 .LBB0_404
	s_and_b64 vcc, exec, s[54:55]
	s_cbranch_vccz .LBB0_407
	s_barrier

; #define PG8_STAGE(bufoff, gbase, voff) do { _Pragma("unroll") for (int _i = 0; _i < 2; ++_i) \
;         __builtin_amdgcn_global_load_lds((const unsigned*)((const char*)(gbase) + (voff)[_i]), (PG8_LAS unsigned*)(lds + (bufoff) + ldsw + _i * 8192), 16, 0, 0); } while (0)
; #define PG8_LDA(dst, b, h) do { _Pragma("unroll") for (int m = 0; m < 4; ++m) _Pragma("unroll") for (int k = 0; k < 2; ++k) dst[m][k] = *(const PG8_LAS bf16x8*)(lds + PG8_SA(b, h) + aoff + m * 2048 + k * 1024); } while (0)
; #define PG8_LDB(dst, b, h) do { _Pragma("unroll") for (int n = 0; n < 2; ++n) _Pragma("unroll") for (int k = 0; k < 2; ++k) dst[n][k] = *(const PG8_LAS bf16x8*)(lds + PG8_SB(b, h) + boff + n * 2048 + k * 1024); } while (0)
; #define PG8_MMA(ai, bj, At, Bt) do { __builtin_amdgcn_s_setprio(1); _Pragma("unroll") for (int m = 0; m < 4; ++m) _Pragma("unroll") for (int n = 0; n < 2; ++n) _Pragma("unroll") for (int k = 0; k < 2; ++k) \
;         acc[ai][bj][m][n] = __builtin_amdgcn_mfma_f32_16x16x32_bf16(Bt[n][k], At[m][k], acc[ai][bj][m][n], 0, 0, 0); __builtin_amdgcn_s_setprio(0); } while (0)
; #define PG8_WAIT_V(n) asm volatile("s_waitcnt vmcnt(" #n ")" ::: "memory")
; #define PG8_WAIT_L(n) asm volatile("s_waitcnt lgkmcnt(" #n ")" ::: "memory")
; #define PG8_BAR __builtin_amdgcn_s_barrier()
; #define PG8_SCHED __builtin_amdgcn_sched_barrier(0)
; template <class Epi, class Sched, bool ALIGN_EPI = false, bool SP2 = false>
; __device__ __forceinline__ void gemm_phase(PG8_LAS unsigned char* lds, const Gemm g, const Sched& S, const Epi& E) {
;     ...
;             const bool last = (t == nt - 2);
;             const char* a1 = cA + (size_t)(t + 1) * kstep;
;             const char* a2 = last ? nA : cA + (size_t)(t + 2) * kstep; const char* b2 = last ? nB : cB + (size_t)(t + 2) * kstep;
;             const char* a3 = a2 + kstep; const char* b3 = b2 + kstep;
;             if (last && has_next) S.a_ready(nxt);
;             if constexpr (SP2) {
;             PG8_LDB(B0, 0, 0); PG8_LDB(B1, 0, 1); PG8_SCHED; PG8_LDA(At, 0, 0); PG8_STAGE(PG8_SA(1, 1), a1 + hstep, voffA);
;             PG8_WAIT_V(8); PG8_WAIT_L(0); PG8_BAR; PG8_MMA(0, 0, At, B0); PG8_MMA(0, 1, At, B1); PG8_BAR; PG8_SCHED;
;             PG8_LDA(At, 0, 1); PG8_STAGE(PG8_SB(0, 0), b2, voffB); PG8_STAGE(PG8_SB(0, 1), b2 + hstep, voffB); PG8_STAGE(PG8_SA(0, 0), a2, voffA);
.LBB0_552:
	ds_read_b128 v[152:155], v149
	ds_read_b128 v[156:159], v149 offset:1024
	ds_read_b128 v[160:163], v149 offset:2048
	ds_read_b128 v[164:167], v149 offset:3072
	ds_read_b128 v[168:171], v150
	ds_read_b128 v[172:175], v150 offset:1024
	ds_read_b128 v[180:183], v150 offset:2048
	ds_read_b128 v[184:187], v150 offset:3072
	s_add_u32 s34, s26, 0x100
	s_addc_u32 s35, s27, 0
	s_cmpk_eq_i32 s67, 0x54
	s_cselect_b32 s45, s7, s35
	s_cselect_b32 s44, s6, s34
	s_cselect_b32 s37, s9, s66
	s_cselect_b32 s36, s8, s65
	v_lshl_add_u64 v[144:145], s[26:27], 0, v[136:137]
	s_add_i32 m0, s29, 0xc000
	ds_read_b128 v[188:191], v151
	ds_read_b128 v[192:195], v151 offset:1024
	ds_read_b128 v[196:199], v151 offset:2048
	ds_read_b128 v[200:203], v151 offset:3072
	ds_read_b128 v[204:207], v151 offset:4096
	ds_read_b128 v[208:211], v151 offset:5120
	ds_read_b128 v[212:215], v151 offset:6144
	ds_read_b128 v[216:219], v151 offset:7168
	global_load_lds_dwordx4 v[144:145], off
	v_lshl_add_u64 v[144:145], s[26:27], 0, v[138:139]
	s_add_i32 m0, s29, 0xe000
	s_nop 0
	global_load_lds_dwordx4 v[144:145], off
	s_waitcnt vmcnt(8)
	s_waitcnt lgkmcnt(0)
	s_barrier
	s_setprio 1
	s_waitcnt lgkmcnt(0)
	v_mfma_f32_16x16x32_bf16 v[124:127], v[152:155], v[188:191], v[124:127]
	v_mfma_f32_16x16x32_bf16 v[120:123], v[160:163], v[188:191], v[120:123]
	v_mfma_f32_16x16x32_bf16 v[108:111], v[160:163], v[196:199], v[108:111]
	v_mfma_f32_16x16x32_bf16 v[116:119], v[152:155], v[196:199], v[116:119]
	v_mfma_f32_16x16x32_bf16 v[100:103], v[152:155], v[204:207], v[100:103]
	v_mfma_f32_16x16x32_bf16 v[92:95], v[160:163], v[204:207], v[92:95]
	v_mfma_f32_16x16x32_bf16 v[76:79], v[160:163], v[212:215], v[76:79]
	v_mfma_f32_16x16x32_bf16 v[84:87], v[152:155], v[212:215], v[84:87]
	v_mfma_f32_16x16x32_bf16 v[84:87], v[156:159], v[216:219], v[84:87]
	v_mfma_f32_16x16x32_bf16 v[76:79], v[164:167], v[216:219], v[76:79]
	v_mfma_f32_16x16x32_bf16 v[92:95], v[164:167], v[208:211], v[92:95]
	v_mfma_f32_16x16x32_bf16 v[100:103], v[156:159], v[208:211], v[100:103]
	v_mfma_f32_16x16x32_bf16 v[116:119], v[156:159], v[200:203], v[116:119]
	v_mfma_f32_16x16x32_bf16 v[108:111], v[164:167], v[200:203], v[108:111]
	v_mfma_f32_16x16x32_bf16 v[120:123], v[164:167], v[192:195], v[120:123]
	v_mfma_f32_16x16x32_bf16 v[124:127], v[156:159], v[192:195], v[124:127]
	s_setprio 0
	s_setprio 1
	v_mfma_f32_16x16x32_bf16 v[112:115], v[168:171], v[188:191], v[112:115]
	v_mfma_f32_16x16x32_bf16 v[104:107], v[180:183], v[188:191], v[104:107]
	v_mfma_f32_16x16x32_bf16 v[88:91], v[180:183], v[196:199], v[88:91]
	v_mfma_f32_16x16x32_bf16 v[96:99], v[168:171], v[196:199], v[96:99]
	v_mfma_f32_16x16x32_bf16 v[80:83], v[168:171], v[204:207], v[80:83]
	v_mfma_f32_16x16x32_bf16 v[72:75], v[180:183], v[204:207], v[72:75]
	v_mfma_f32_16x16x32_bf16 v[64:67], v[180:183], v[212:215], v[64:67]
	v_mfma_f32_16x16x32_bf16 v[68:71], v[168:171], v[212:215], v[68:71]
	v_mfma_f32_16x16x32_bf16 v[68:71], v[172:175], v[216:219], v[68:71]
	v_mfma_f32_16x16x32_bf16 v[64:67], v[184:187], v[216:219], v[64:67]
	v_mfma_f32_16x16x32_bf16 v[72:75], v[184:187], v[208:211], v[72:75]
	v_mfma_f32_16x16x32_bf16 v[80:83], v[172:175], v[208:211], v[80:83]
	v_mfma_f32_16x16x32_bf16 v[96:99], v[172:175], v[200:203], v[96:99]
	v_mfma_f32_16x16x32_bf16 v[88:91], v[184:187], v[200:203], v[88:91]
	v_mfma_f32_16x16x32_bf16 v[104:107], v[184:187], v[192:195], v[104:107]
	v_mfma_f32_16x16x32_bf16 v[112:115], v[172:175], v[192:195], v[112:115]
	s_setprio 0
	s_barrier
	s_add_i32 s26, s55, s1
	v_lshl_add_u64 v[144:145], s[36:37], 0, v[130:131]
	s_mov_b32 m0, s26
	ds_read_b128 v[188:191], v151 offset:16384
	ds_read_b128 v[192:195], v151 offset:17408
	ds_read_b128 v[196:199], v151 offset:18432
	ds_read_b128 v[200:203], v151 offset:19456
	ds_read_b128 v[204:207], v151 offset:20480
	ds_read_b128 v[208:211], v151 offset:21504
	ds_read_b128 v[212:215], v151 offset:22528
	ds_read_b128 v[216:219], v151 offset:23552
	global_load_lds_dwordx4 v[144:145], off
	s_add_i32 m0, s26, 0x2000
	s_add_u32 s26, s36, 0x160000
	v_lshl_add_u64 v[176:177], s[36:37], 0, v[134:135]
	s_addc_u32 s27, s37, 0
	s_add_i32 s30, s56, s1
	global_load_lds_dwordx4 v[176:177], off
	v_lshl_add_u64 v[220:221], s[26:27], 0, v[130:131]
	s_mov_b32 m0, s30
	v_lshl_add_u64 v[222:223], s[44:45], 0, v[132:133]
	global_load_lds_dwordx4 v[220:221], off
	v_lshl_add_u64 v[220:221], s[26:27], 0, v[134:135]
	s_add_i32 m0, s30, 0x2000
	s_nop 0
	global_load_lds_dwordx4 v[220:221], off
	v_lshl_add_u64 v[220:221], s[44:45], 0, v[128:129]
	s_mov_b32 m0, s29
	s_nop 0
	global_load_lds_dwordx4 v[220:221], off
	s_mov_b32 m0, s33
	s_nop 0
	global_load_lds_dwordx4 v[222:223], off
	s_waitcnt vmcnt(8)
	s_waitcnt lgkmcnt(0)
	s_barrier
; #define PG8_STAGE(bufoff, gbase, voff) do { _Pragma("unroll") for (int _i = 0; _i < 2; ++_i) \
;         __builtin_amdgcn_global_load_lds((const unsigned*)((const char*)(gbase) + (voff)[_i]), (PG8_LAS unsigned*)(lds + (bufoff) + ldsw + _i * 8192), 16, 0, 0); } while (0)
; #define PG8_LDA(dst, b, h) do { _Pragma("unroll") for (int m = 0; m < 4; ++m) _Pragma("unroll") for (int k = 0; k < 2; ++k) dst[m][k] = *(const PG8_LAS bf16x8*)(lds + PG8_SA(b, h) + aoff + m * 2048 + k * 1024); } while (0)
; #define PG8_LDB(dst, b, h) do { _Pragma("unroll") for (int n = 0; n < 2; ++n) _Pragma("unroll") for (int k = 0; k < 2; ++k) dst[n][k] = *(const PG8_LAS bf16x8*)(lds + PG8_SB(b, h) + boff + n * 2048 + k * 1024); } while (0)
; #define PG8_MMA(ai, bj, At, Bt) do { __builtin_amdgcn_s_setprio(1); _Pragma("unroll") for (int m = 0; m < 4; ++m) _Pragma("unroll") for (int n = 0; n < 2; ++n) _Pragma("unroll") for (int k = 0; k < 2; ++k) \
;         acc[ai][bj][m][n] = __builtin_amdgcn_mfma_f32_16x16x32_bf16(Bt[n][k], At[m][k], acc[ai][bj][m][n], 0, 0, 0); __builtin_amdgcn_s_setprio(0); } while (0)
; #define PG8_WAIT_V(n) asm volatile("s_waitcnt vmcnt(" #n ")" ::: "memory")
; #define PG8_WAIT_L(n) asm volatile("s_waitcnt lgkmcnt(" #n ")" ::: "memory")
; #define PG8_BAR __builtin_amdgcn_s_barrier()
; #define PG8_SCHED __builtin_amdgcn_sched_barrier(0)
; template <class Epi, class Sched, bool ALIGN_EPI = false, bool SP2 = false>
; __device__ __forceinline__ void gemm_phase(PG8_LAS unsigned char* lds, const Gemm g, const Sched& S, const Epi& E) {
;     ...
;             PG8_WAIT_V(8); PG8_WAIT_L(0); PG8_BAR; PG8_MMA(1, 0, At, B0); PG8_MMA(1, 1, At, B1); PG8_BAR; PG8_SCHED;
;             PG8_LDB(B0, 1, 0); PG8_LDB(B1, 1, 1); PG8_SCHED; PG8_LDA(At, 1, 0); PG8_STAGE(PG8_SA(0, 1), a2 + hstep, voffA);
;             PG8_WAIT_V(8); PG8_WAIT_L(0); PG8_BAR; PG8_MMA(0, 0, At, B0); PG8_MMA(0, 1, At, B1); PG8_BAR; PG8_SCHED;
	s_setprio 1
	s_waitcnt lgkmcnt(0)
	v_mfma_f32_16x16x32_bf16 v[60:63], v[152:155], v[188:191], v[60:63]
	v_mfma_f32_16x16x32_bf16 v[56:59], v[160:163], v[188:191], v[56:59]
	v_mfma_f32_16x16x32_bf16 v[44:47], v[160:163], v[196:199], v[44:47]
	v_mfma_f32_16x16x32_bf16 v[52:55], v[152:155], v[196:199], v[52:55]
	v_mfma_f32_16x16x32_bf16 v[36:39], v[152:155], v[204:207], v[36:39]
	v_mfma_f32_16x16x32_bf16 v[28:31], v[160:163], v[204:207], v[28:31]
	v_mfma_f32_16x16x32_bf16 v[12:15], v[160:163], v[212:215], v[12:15]
	v_mfma_f32_16x16x32_bf16 v[20:23], v[152:155], v[212:215], v[20:23]
	v_mfma_f32_16x16x32_bf16 v[20:23], v[156:159], v[216:219], v[20:23]
	v_mfma_f32_16x16x32_bf16 v[12:15], v[164:167], v[216:219], v[12:15]
	v_mfma_f32_16x16x32_bf16 v[28:31], v[164:167], v[208:211], v[28:31]
	v_mfma_f32_16x16x32_bf16 v[36:39], v[156:159], v[208:211], v[36:39]
	v_mfma_f32_16x16x32_bf16 v[52:55], v[156:159], v[200:203], v[52:55]
	v_mfma_f32_16x16x32_bf16 v[44:47], v[164:167], v[200:203], v[44:47]
	v_mfma_f32_16x16x32_bf16 v[56:59], v[164:167], v[192:195], v[56:59]
	v_mfma_f32_16x16x32_bf16 v[60:63], v[156:159], v[192:195], v[60:63]
	s_setprio 0
	s_setprio 1
	v_mfma_f32_16x16x32_bf16 v[48:51], v[168:171], v[188:191], v[48:51]
	v_mfma_f32_16x16x32_bf16 v[40:43], v[180:183], v[188:191], v[40:43]
	v_mfma_f32_16x16x32_bf16 v[24:27], v[180:183], v[196:199], v[24:27]
	v_mfma_f32_16x16x32_bf16 v[32:35], v[168:171], v[196:199], v[32:35]
	v_mfma_f32_16x16x32_bf16 v[16:19], v[168:171], v[204:207], v[16:19]
	v_mfma_f32_16x16x32_bf16 v[8:11], v[180:183], v[204:207], v[8:11]
	v_mfma_f32_16x16x32_bf16 v[0:3], v[180:183], v[212:215], v[0:3]
	v_mfma_f32_16x16x32_bf16 v[4:7], v[168:171], v[212:215], v[4:7]
	v_mfma_f32_16x16x32_bf16 v[4:7], v[172:175], v[216:219], v[4:7]
	v_mfma_f32_16x16x32_bf16 v[0:3], v[184:187], v[216:219], v[0:3]
	v_mfma_f32_16x16x32_bf16 v[8:11], v[184:187], v[208:211], v[8:11]
	v_mfma_f32_16x16x32_bf16 v[16:19], v[172:175], v[208:211], v[16:19]
	v_mfma_f32_16x16x32_bf16 v[32:35], v[172:175], v[200:203], v[32:35]
	v_mfma_f32_16x16x32_bf16 v[24:27], v[184:187], v[200:203], v[24:27]
	v_mfma_f32_16x16x32_bf16 v[40:43], v[184:187], v[192:195], v[40:43]
	v_mfma_f32_16x16x32_bf16 v[48:51], v[172:175], v[192:195], v[48:51]
	s_setprio 0
	s_barrier
	s_add_i32 s30, 0, 0x18000
	s_add_i32 s31, 0, 0x1c000
	v_add_u32_e32 v164, s30, v147
	v_add_u32_e32 v184, s31, v147
	ds_read_b128 v[152:155], v164
	ds_read_b128 v[156:159], v164 offset:1024
	ds_read_b128 v[160:163], v164 offset:2048
	ds_read_b128 v[164:167], v164 offset:3072
	ds_read_b128 v[168:171], v184
	ds_read_b128 v[172:175], v184 offset:1024
	ds_read_b128 v[180:183], v184 offset:2048
	ds_read_b128 v[184:187], v184 offset:3072
	s_add_u32 s26, s44, 0x160000
	s_addc_u32 s27, s45, 0
	s_mov_b32 m0, s46
	v_lshl_add_u64 v[224:225], s[26:27], 0, v[128:129]
	ds_read_b128 v[188:191], v151 offset:32768
	ds_read_b128 v[192:195], v151 offset:33792
	ds_read_b128 v[196:199], v151 offset:34816
	ds_read_b128 v[200:203], v151 offset:35840
	ds_read_b128 v[204:207], v151 offset:36864
	ds_read_b128 v[208:211], v151 offset:37888
	ds_read_b128 v[212:215], v151 offset:38912
	ds_read_b128 v[216:219], v151 offset:39936
	global_load_lds_dwordx4 v[224:225], off
	v_lshl_add_u64 v[224:225], s[26:27], 0, v[132:133]
	s_mov_b32 m0, s47
	s_nop 0
	global_load_lds_dwordx4 v[224:225], off
	s_waitcnt vmcnt(8)
	s_waitcnt lgkmcnt(0)
	s_barrier
	s_setprio 1
	s_waitcnt lgkmcnt(0)
	v_mfma_f32_16x16x32_bf16 v[124:127], v[152:155], v[188:191], v[124:127]
	v_mfma_f32_16x16x32_bf16 v[120:123], v[160:163], v[188:191], v[120:123]
	v_mfma_f32_16x16x32_bf16 v[108:111], v[160:163], v[196:199], v[108:111]
	v_mfma_f32_16x16x32_bf16 v[116:119], v[152:155], v[196:199], v[116:119]
	v_mfma_f32_16x16x32_bf16 v[100:103], v[152:155], v[204:207], v[100:103]
	v_mfma_f32_16x16x32_bf16 v[92:95], v[160:163], v[204:207], v[92:95]
	v_mfma_f32_16x16x32_bf16 v[76:79], v[160:163], v[212:215], v[76:79]
	v_mfma_f32_16x16x32_bf16 v[84:87], v[152:155], v[212:215], v[84:87]
	v_mfma_f32_16x16x32_bf16 v[84:87], v[156:159], v[216:219], v[84:87]
	v_mfma_f32_16x16x32_bf16 v[76:79], v[164:167], v[216:219], v[76:79]
	v_mfma_f32_16x16x32_bf16 v[92:95], v[164:167], v[208:211], v[92:95]
	v_mfma_f32_16x16x32_bf16 v[100:103], v[156:159], v[208:211], v[100:103]
	v_mfma_f32_16x16x32_bf16 v[116:119], v[156:159], v[200:203], v[116:119]
	v_mfma_f32_16x16x32_bf16 v[108:111], v[164:167], v[200:203], v[108:111]
	v_mfma_f32_16x16x32_bf16 v[120:123], v[164:167], v[192:195], v[120:123]
	v_mfma_f32_16x16x32_bf16 v[124:127], v[156:159], v[192:195], v[124:127]
	s_setprio 0
	s_setprio 1
	v_mfma_f32_16x16x32_bf16 v[112:115], v[168:171], v[188:191], v[112:115]
	v_mfma_f32_16x16x32_bf16 v[104:107], v[180:183], v[188:191], v[104:107]
	v_mfma_f32_16x16x32_bf16 v[88:91], v[180:183], v[196:199], v[88:91]
	v_mfma_f32_16x16x32_bf16 v[96:99], v[168:171], v[196:199], v[96:99]
	v_mfma_f32_16x16x32_bf16 v[80:83], v[168:171], v[204:207], v[80:83]
	v_mfma_f32_16x16x32_bf16 v[72:75], v[180:183], v[204:207], v[72:75]
	v_mfma_f32_16x16x32_bf16 v[64:67], v[180:183], v[212:215], v[64:67]
	v_mfma_f32_16x16x32_bf16 v[68:71], v[168:171], v[212:215], v[68:71]
	v_mfma_f32_16x16x32_bf16 v[68:71], v[172:175], v[216:219], v[68:71]
	v_mfma_f32_16x16x32_bf16 v[64:67], v[184:187], v[216:219], v[64:67]
	v_mfma_f32_16x16x32_bf16 v[72:75], v[184:187], v[208:211], v[72:75]
	v_mfma_f32_16x16x32_bf16 v[80:83], v[172:175], v[208:211], v[80:83]
	v_mfma_f32_16x16x32_bf16 v[96:99], v[172:175], v[200:203], v[96:99]
	v_mfma_f32_16x16x32_bf16 v[88:91], v[184:187], v[200:203], v[88:91]
	v_mfma_f32_16x16x32_bf16 v[104:107], v[184:187], v[192:195], v[104:107]
	v_mfma_f32_16x16x32_bf16 v[112:115], v[172:175], v[192:195], v[112:115]
	s_setprio 0
	s_barrier
; #define PG8_STAGE(bufoff, gbase, voff) do { _Pragma("unroll") for (int _i = 0; _i < 2; ++_i) \
;         __builtin_amdgcn_global_load_lds((const unsigned*)((const char*)(gbase) + (voff)[_i]), (PG8_LAS unsigned*)(lds + (bufoff) + ldsw + _i * 8192), 16, 0, 0); } while (0)
; #define PG8_LDA(dst, b, h) do { _Pragma("unroll") for (int m = 0; m < 4; ++m) _Pragma("unroll") for (int k = 0; k < 2; ++k) dst[m][k] = *(const PG8_LAS bf16x8*)(lds + PG8_SA(b, h) + aoff + m * 2048 + k * 1024); } while (0)
; #define PG8_MMA(ai, bj, At, Bt) do { __builtin_amdgcn_s_setprio(1); _Pragma("unroll") for (int m = 0; m < 4; ++m) _Pragma("unroll") for (int n = 0; n < 2; ++n) _Pragma("unroll") for (int k = 0; k < 2; ++k) \
;         acc[ai][bj][m][n] = __builtin_amdgcn_mfma_f32_16x16x32_bf16(Bt[n][k], At[m][k], acc[ai][bj][m][n], 0, 0, 0); __builtin_amdgcn_s_setprio(0); } while (0)
; #define PG8_WAIT_V(n) asm volatile("s_waitcnt vmcnt(" #n ")" ::: "memory")
; #define PG8_WAIT_L(n) asm volatile("s_waitcnt lgkmcnt(" #n ")" ::: "memory")
; #define PG8_BAR __builtin_amdgcn_s_barrier()
; #define PG8_SCHED __builtin_amdgcn_sched_barrier(0)
; template <class Epi, class Sched, bool ALIGN_EPI = false, bool SP2 = false>
; __device__ __forceinline__ void gemm_phase(PG8_LAS unsigned char* lds, const Gemm g, const Sched& S, const Epi& E) {
;     ...
;         for (int t = 0; t < nt; t += 2) {
;             const bool last = (t == nt - 2);
;             const char* a1 = cA + (size_t)(t + 1) * kstep;
;             const char* a2 = last ? nA : cA + (size_t)(t + 2) * kstep; const char* b2 = last ? nB : cB + (size_t)(t + 2) * kstep;
;     ...
;             PG8_LDA(At, 1, 1); PG8_STAGE(PG8_SB(1, 0), b3, voffB); PG8_STAGE(PG8_SB(1, 1), b3 + hstep, voffB); PG8_STAGE(PG8_SA(1, 0), a3, voffA);
;             PG8_WAIT_V(8); PG8_WAIT_L(0); PG8_BAR; PG8_MMA(1, 0, At, B0); PG8_MMA(1, 1, At, B1); PG8_BAR; PG8_SCHED;
	s_add_i32 s26, s30, s1
	v_lshl_add_u64 v[144:145], v[144:145], 0, s[10:11]
	s_mov_b32 m0, s26
	ds_read_b128 v[188:191], v151 offset:49152
	ds_read_b128 v[192:195], v151 offset:50176
	ds_read_b128 v[196:199], v151 offset:51200
	ds_read_b128 v[200:203], v151 offset:52224
	ds_read_b128 v[204:207], v151 offset:53248
	ds_read_b128 v[208:211], v151 offset:54272
	ds_read_b128 v[212:215], v151 offset:55296
	ds_read_b128 v[216:219], v151 offset:56320
	global_load_lds_dwordx4 v[144:145], off
	s_add_i32 m0, s26, 0x2000
	s_add_u32 s26, s36, 0x160080
	v_lshl_add_u64 v[144:145], v[176:177], 0, s[10:11]
	s_addc_u32 s27, s37, 0
	s_add_i32 s30, s31, s1
	global_load_lds_dwordx4 v[144:145], off
	v_lshl_add_u64 v[144:145], s[26:27], 0, v[130:131]
	s_mov_b32 m0, s30
	s_nop 0
	global_load_lds_dwordx4 v[144:145], off
	v_lshl_add_u64 v[144:145], s[26:27], 0, v[134:135]
	s_add_i32 m0, s30, 0x2000
	s_nop 0
	global_load_lds_dwordx4 v[144:145], off
	v_lshl_add_u64 v[144:145], v[220:221], 0, s[10:11]
	s_mov_b32 m0, s53
	s_nop 0
	global_load_lds_dwordx4 v[144:145], off
	v_lshl_add_u64 v[144:145], v[222:223], 0, s[10:11]
	s_mov_b32 m0, s54
	s_nop 0
	global_load_lds_dwordx4 v[144:145], off
	s_waitcnt vmcnt(8)
	s_waitcnt lgkmcnt(0)
	s_barrier
	s_setprio 1
	s_waitcnt lgkmcnt(0)
	v_mfma_f32_16x16x32_bf16 v[60:63], v[152:155], v[188:191], v[60:63]
	v_mfma_f32_16x16x32_bf16 v[56:59], v[160:163], v[188:191], v[56:59]
	v_mfma_f32_16x16x32_bf16 v[44:47], v[160:163], v[196:199], v[44:47]
	v_mfma_f32_16x16x32_bf16 v[52:55], v[152:155], v[196:199], v[52:55]
	v_mfma_f32_16x16x32_bf16 v[36:39], v[152:155], v[204:207], v[36:39]
	v_mfma_f32_16x16x32_bf16 v[28:31], v[160:163], v[204:207], v[28:31]
	v_mfma_f32_16x16x32_bf16 v[12:15], v[160:163], v[212:215], v[12:15]
	v_mfma_f32_16x16x32_bf16 v[20:23], v[152:155], v[212:215], v[20:23]
	v_mfma_f32_16x16x32_bf16 v[20:23], v[156:159], v[216:219], v[20:23]
	v_mfma_f32_16x16x32_bf16 v[12:15], v[164:167], v[216:219], v[12:15]
	v_mfma_f32_16x16x32_bf16 v[28:31], v[164:167], v[208:211], v[28:31]
	v_mfma_f32_16x16x32_bf16 v[36:39], v[156:159], v[208:211], v[36:39]
	v_mfma_f32_16x16x32_bf16 v[52:55], v[156:159], v[200:203], v[52:55]
	v_mfma_f32_16x16x32_bf16 v[44:47], v[164:167], v[200:203], v[44:47]
	v_mfma_f32_16x16x32_bf16 v[56:59], v[164:167], v[192:195], v[56:59]
	v_mfma_f32_16x16x32_bf16 v[60:63], v[156:159], v[192:195], v[60:63]
	s_setprio 0
	s_setprio 1
	v_mfma_f32_16x16x32_bf16 v[48:51], v[168:171], v[188:191], v[48:51]
	v_mfma_f32_16x16x32_bf16 v[40:43], v[180:183], v[188:191], v[40:43]
	v_mfma_f32_16x16x32_bf16 v[24:27], v[180:183], v[196:199], v[24:27]
	v_mfma_f32_16x16x32_bf16 v[32:35], v[168:171], v[196:199], v[32:35]
	v_mfma_f32_16x16x32_bf16 v[16:19], v[168:171], v[204:207], v[16:19]
	v_mfma_f32_16x16x32_bf16 v[8:11], v[180:183], v[204:207], v[8:11]
	v_mfma_f32_16x16x32_bf16 v[0:3], v[180:183], v[212:215], v[0:3]
	v_mfma_f32_16x16x32_bf16 v[4:7], v[168:171], v[212:215], v[4:7]
	v_mfma_f32_16x16x32_bf16 v[4:7], v[172:175], v[216:219], v[4:7]
	v_mfma_f32_16x16x32_bf16 v[0:3], v[184:187], v[216:219], v[0:3]
	v_mfma_f32_16x16x32_bf16 v[8:11], v[184:187], v[208:211], v[8:11]
	v_mfma_f32_16x16x32_bf16 v[16:19], v[172:175], v[208:211], v[16:19]
	v_mfma_f32_16x16x32_bf16 v[32:35], v[172:175], v[200:203], v[32:35]
	v_mfma_f32_16x16x32_bf16 v[24:27], v[184:187], v[200:203], v[24:27]
	v_mfma_f32_16x16x32_bf16 v[40:43], v[184:187], v[192:195], v[40:43]
	v_mfma_f32_16x16x32_bf16 v[48:51], v[172:175], v[192:195], v[48:51]
	s_setprio 0
	s_barrier
	s_add_i32 s67, s67, 2
	s_add_u32 s65, s65, 0x100
	s_addc_u32 s66, s66, 0
	s_cmpk_gt_u32 s67, 0x55
	s_mov_b64 s[26:27], s[34:35]
	s_cbranch_scc0 .LBB0_552
; __device__ __forceinline__ unsigned cvt_pk_bf16(float lo, float hi) { unsigned r; asm volatile("v_cvt_pk_bf16_f32 %0, %1, %2" : "=v"(r) : "v"(lo), "v"(hi)); return r; }
; #define PG8_WAIT_V(n) asm volatile("s_waitcnt vmcnt(" #n ")" ::: "memory")
; #define PG8_BAR __builtin_amdgcn_s_barrier()
;     __device__ __forceinline__ void operator()(const f32x4 (&acc)[2][2][4][2], const Unit& u, int wr, int wc, int fr, int fq) const {
;         const int row0 = u.pm * BM + wr * 64 + fr; const int col0 = u.pn * BM + wc * 32 + 8 * fq;
; #pragma unroll
;         for (int ai = 0; ai < 2; ++ai)
; #pragma unroll
;             for (int m = 0; m < 4; ++m) { bf16_t* rowp = O + (size_t)(row0 + ai * HALF + m * 16) * ldc + col0;
; #pragma unroll
;                 for (int bj = 0; bj < 2; ++bj) { const f32x4 v0 = acc[ai][bj][m][0], v1 = acc[ai][bj][m][1];
;                     u32x4 w; w.x = cvt_pk_bf16(v0[0], v0[1]); w.y = cvt_pk_bf16(v0[2], v0[3]); w.z = cvt_pk_bf16(v1[0], v1[1]); w.w = cvt_pk_bf16(v1[2], v1[3]);
;                     *(u32x4*)(rowp + bj * HALF) = w; } }
;     }
; template <class Epi, class Sched, bool ALIGN_EPI = false, bool SP2 = false>
; __device__ __forceinline__ void gemm_phase(PG8_LAS unsigned char* lds, const Gemm g, const Sched& S, const Epi& E) {
;     ...
;         if constexpr (!Epi::AFTER_DRAIN) { E(acc, cur, wr, wc, fr, fq); S.done(cur); }
;         if (!has_next) break;
; #pragma unroll
;         for (int a = 0; a < 2; ++a)
; #pragma unroll
;             for (int b = 0; b < 2; ++b)
; #pragma unroll
;                 for (int m = 0; m < 4; ++m)
; #pragma unroll
;                     for (int n = 0; n < 2; ++n) acc[a][b][m][n] = (f32x4){0.f, 0.f, 0.f, 0.f};
;         cur = nxt; cA = nA; cB = nB; ++ui;
;         if constexpr (ALIGN_EPI) { if (wr == 1) PG8_BAR; }
;     }
;     PG8_WAIT_V(0);
;     if constexpr (!ALIGN_EPI) { if (wr == 0) PG8_BAR; }
;     PG8_BAR;
	v_lshl_add_u32 v152, s63, 8, v146
	v_lshl_or_b32 v144, s64, 8, v148
	v_ashrrev_i32_e32 v153, 31, v152
	v_ashrrev_i32_e32 v145, 31, v144
	v_lshlrev_b64 v[154:155], 12, v[152:153]
	v_lshl_add_u64 v[154:155], s[18:19], 0, v[154:155]
	v_lshlrev_b64 v[156:157], 1, v[144:145]
	v_lshl_add_u64 v[144:145], v[154:155], 0, v[156:157]
	v_cvt_pk_bf16_f32 v124, v124, v125
	v_cvt_pk_bf16_f32 v125, v126, v127
	v_cvt_pk_bf16_f32 v126, v120, v121
	v_cvt_pk_bf16_f32 v127, v122, v123
	global_store_dwordx4 v[144:145], v[124:127], off
	v_cvt_pk_bf16_f32 v112, v112, v113
	v_cvt_pk_bf16_f32 v113, v114, v115
	v_cvt_pk_bf16_f32 v114, v104, v105
	v_or_b32_e32 v104, 16, v152
	v_ashrrev_i32_e32 v105, 31, v104
	v_lshlrev_b64 v[104:105], 12, v[104:105]
	v_lshl_add_u64 v[104:105], s[18:19], 0, v[104:105]
	v_cvt_pk_bf16_f32 v115, v106, v107
	global_store_dwordx4 v[144:145], v[112:115], off offset:256
	s_mov_b32 s64, s61
	s_mov_b32 s63, s62
	v_lshl_add_u64 v[112:113], v[104:105], 0, v[156:157]
	v_cvt_pk_bf16_f32 v104, v116, v117
	v_cvt_pk_bf16_f32 v105, v118, v119
	v_cvt_pk_bf16_f32 v106, v108, v109
	v_cvt_pk_bf16_f32 v107, v110, v111
	global_store_dwordx4 v[112:113], v[104:107], off
	v_cvt_pk_bf16_f32 v96, v96, v97
	v_cvt_pk_bf16_f32 v97, v98, v99
	v_cvt_pk_bf16_f32 v98, v88, v89
	v_or_b32_e32 v88, 32, v152
	v_ashrrev_i32_e32 v89, 31, v88
	v_lshlrev_b64 v[88:89], 12, v[88:89]
	v_lshl_add_u64 v[88:89], s[18:19], 0, v[88:89]
	v_cvt_pk_bf16_f32 v99, v90, v91
	global_store_dwordx4 v[112:113], v[96:99], off offset:256
	s_mov_b64 s[34:35], s[8:9]
	s_mov_b64 s[26:27], s[6:7]
	v_lshl_add_u64 v[96:97], v[88:89], 0, v[156:157]
	v_cvt_pk_bf16_f32 v88, v100, v101
	v_cvt_pk_bf16_f32 v89, v102, v103
	v_cvt_pk_bf16_f32 v90, v92, v93
	v_cvt_pk_bf16_f32 v91, v94, v95
	global_store_dwordx4 v[96:97], v[88:91], off
	v_cvt_pk_bf16_f32 v80, v80, v81
	v_cvt_pk_bf16_f32 v81, v82, v83
	v_cvt_pk_bf16_f32 v82, v72, v73
	v_or_b32_e32 v72, 48, v152
	v_ashrrev_i32_e32 v73, 31, v72
	v_lshlrev_b64 v[72:73], 12, v[72:73]
	v_lshl_add_u64 v[72:73], s[18:19], 0, v[72:73]
	v_cvt_pk_bf16_f32 v83, v74, v75
	global_store_dwordx4 v[96:97], v[80:83], off offset:256
	s_nop 1
	v_lshl_add_u64 v[80:81], v[72:73], 0, v[156:157]
	v_cvt_pk_bf16_f32 v72, v84, v85
	v_cvt_pk_bf16_f32 v73, v86, v87
	v_cvt_pk_bf16_f32 v74, v76, v77
	v_cvt_pk_bf16_f32 v75, v78, v79
	global_store_dwordx4 v[80:81], v[72:75], off
	v_cvt_pk_bf16_f32 v68, v68, v69
	v_cvt_pk_bf16_f32 v69, v70, v71
	v_cvt_pk_bf16_f32 v70, v64, v65
	v_cvt_pk_bf16_f32 v71, v66, v67
	global_store_dwordx4 v[80:81], v[68:71], off offset:256
	v_cvt_pk_bf16_f32 v60, v60, v61
	v_cvt_pk_bf16_f32 v61, v62, v63
	v_cvt_pk_bf16_f32 v62, v56, v57
	v_add_co_u32_e32 v56, vcc, s57, v144
	v_lshl_add_u64 v[64:65], v[144:145], 0, s[16:17]
	s_nop 0
	v_addc_co_u32_e32 v57, vcc, 0, v145, vcc
	v_cvt_pk_bf16_f32 v63, v58, v59
	global_store_dwordx4 v[56:57], v[60:63], off
	v_cvt_pk_bf16_f32 v48, v48, v49
	v_cvt_pk_bf16_f32 v49, v50, v51
	v_cvt_pk_bf16_f32 v50, v40, v41
	v_cvt_pk_bf16_f32 v51, v42, v43
	global_store_dwordx4 v[64:65], v[48:51], off offset:256
	v_cvt_pk_bf16_f32 v40, v52, v53
	v_cvt_pk_bf16_f32 v41, v54, v55
	v_cvt_pk_bf16_f32 v42, v44, v45
	v_add_co_u32_e32 v44, vcc, s58, v144
	s_nop 0
	v_lshl_add_u64 v[48:49], v[144:145], 0, s[20:21]
	v_addc_co_u32_e32 v45, vcc, 0, v145, vcc
	v_cvt_pk_bf16_f32 v43, v46, v47
	global_store_dwordx4 v[44:45], v[40:43], off
	v_cvt_pk_bf16_f32 v32, v32, v33
	v_cvt_pk_bf16_f32 v33, v34, v35
	v_cvt_pk_bf16_f32 v34, v24, v25
	v_cvt_pk_bf16_f32 v35, v26, v27
	global_store_dwordx4 v[48:49], v[32:35], off offset:256
	v_cvt_pk_bf16_f32 v24, v36, v37
	v_cvt_pk_bf16_f32 v25, v38, v39
	v_cvt_pk_bf16_f32 v26, v28, v29
	v_add_co_u32_e32 v28, vcc, s59, v144
	s_nop 0
	v_lshl_add_u64 v[32:33], v[144:145], 0, s[22:23]
	v_addc_co_u32_e32 v29, vcc, 0, v145, vcc
	v_cvt_pk_bf16_f32 v27, v30, v31
	global_store_dwordx4 v[28:29], v[24:27], off
	v_cvt_pk_bf16_f32 v16, v16, v17
	v_cvt_pk_bf16_f32 v17, v18, v19
	v_cvt_pk_bf16_f32 v18, v8, v9
	v_cvt_pk_bf16_f32 v19, v10, v11
	global_store_dwordx4 v[32:33], v[16:19], off offset:256
	v_cvt_pk_bf16_f32 v8, v20, v21
	v_cvt_pk_bf16_f32 v9, v22, v23
	v_cvt_pk_bf16_f32 v10, v12, v13
	v_add_co_u32_e32 v12, vcc, s60, v144
	s_nop 0
	v_lshl_add_u64 v[16:17], v[144:145], 0, s[24:25]
	v_addc_co_u32_e32 v13, vcc, 0, v145, vcc
	s_and_b64 vcc, exec, s[4:5]
	v_cvt_pk_bf16_f32 v11, v14, v15
	global_store_dwordx4 v[12:13], v[8:11], off
	v_cvt_pk_bf16_f32 v4, v4, v5
	v_cvt_pk_bf16_f32 v5, v6, v7
	v_cvt_pk_bf16_f32 v6, v0, v1
	v_cvt_pk_bf16_f32 v7, v2, v3
	global_store_dwordx4 v[16:17], v[4:7], off offset:256
	s_cbranch_vccz .LBB0_541
	s_waitcnt vmcnt(0)
	s_cmpk_gt_u32 s0, 0xff
	s_cbranch_scc1 .LBB0_556
	s_barrier
